# peel first K-loop iteration (C=0 in first MFMAs) instead of zeroing 128 accumulator registers per tile; on top of attention q_gain hoist
# speedup vs baseline: 1.0091x; 1.0091x over previous
; #define PG8_STAGE(bufoff, gbase, voff) do { _Pragma("unroll") for (int _i = 0; _i < 2; ++_i) \
;         __builtin_amdgcn_global_load_lds((const unsigned*)((const char*)(gbase) + (voff)[_i]), (PG8_LAS unsigned*)(lds + (bufoff) + ldsw + _i * 8192), 16, 0, 0); } while (0)
; #define PG8_LDA(dst, b, h) do { _Pragma("unroll") for (int m = 0; m < 4; ++m) _Pragma("unroll") for (int k = 0; k < 2; ++k) dst[m][k] = *(const PG8_LAS bf16x8*)(lds + PG8_SA(b, h) + aoff + m * 2048 + k * 1024); } while (0)
; #define PG8_LDB(dst, b, h) do { _Pragma("unroll") for (int n = 0; n < 2; ++n) _Pragma("unroll") for (int k = 0; k < 2; ++k) dst[n][k] = *(const PG8_LAS bf16x8*)(lds + PG8_SB(b, h) + boff + n * 2048 + k * 1024); } while (0)
; #define PG8_MMA(ai, bj, At, Bt) do { __builtin_amdgcn_s_setprio(1); _Pragma("unroll") for (int m = 0; m < 4; ++m) _Pragma("unroll") for (int n = 0; n < 2; ++n) _Pragma("unroll") for (int k = 0; k < 2; ++k) \
;         acc[ai][bj][m][n] = __builtin_amdgcn_mfma_f32_16x16x32_bf16(Bt[n][k], At[m][k], acc[ai][bj][m][n], 0, 0, 0); __builtin_amdgcn_s_setprio(0); } while (0)
; #define PG8_WAIT_V(n) asm volatile("s_waitcnt vmcnt(" #n ")" ::: "memory")
; #define PG8_WAIT_L(n) asm volatile("s_waitcnt lgkmcnt(" #n ")" ::: "memory")
; #define PG8_BAR __builtin_amdgcn_s_barrier()
; #define PG8_SCHED __builtin_amdgcn_sched_barrier(0)
; template <class Epi, class Sched, bool ALIGN_EPI = false, bool SP2 = false>
; __device__ __forceinline__ void gemm_phase(PG8_LAS unsigned char* lds, const Gemm g, const Sched& S, const Epi& E, int wave_s) {
;     ...
;             PG8_LDB(B0, 0, 0); PG8_LDB(B1, 0, 1); PG8_SCHED; PG8_LDA(At, 0, 0); PG8_STAGE(PG8_SA(1, 1), a1 + hstepA, voffA);
;             PG8_WAIT_V(8); PG8_WAIT_L(0); PG8_BAR; PG8_MMA(0, 0, At, B0); PG8_MMA(0, 1, At, B1); PG8_BAR; PG8_SCHED;
;             PG8_LDA(At, 0, 1); PG8_STAGE(PG8_SB(0, 0), b2, voffB); PG8_STAGE(PG8_SB(0, 1), b2 + hstepB, voffB); PG8_STAGE(PG8_SA(0, 0), a2, voffA);
;             PG8_WAIT_V(8); PG8_WAIT_L(0); PG8_BAR; PG8_MMA(1, 0, At, B0); PG8_MMA(1, 1, At, B1); PG8_BAR; PG8_SCHED;
.LBB0_313:
	s_ashr_i32 s29, s28, 31
	s_lshl_b64 s[2:3], s[28:29], 18
	s_add_u32 s96, s22, s2
	s_addc_u32 s97, s23, s3
	s_and_b64 s[2:3], s[4:5], exec
	s_cselect_b32 s2, s97, s31
	s_cselect_b32 s3, s96, s30
	s_add_u32 s4, s40, 0x80080
	s_addc_u32 s5, s41, 0
	s_add_u32 s29, s30, 0x100
	s_addc_u32 s81, s31, 0
	s_mov_b32 s84, -2
	s_add_u32 s30, s4, 0xfff80080
	s_addc_u32 s31, s5, -1
	s_add_i32 s85, 0, 0x10000
	s_cmp_eq_u32 s84, 4
	s_cselect_b32 s41, s91, s31
	s_cselect_b32 s40, s90, s30
	s_cselect_b32 s31, s2, s81
	s_cselect_b32 s30, s3, s29
	s_add_i32 s89, 0, 0x14000
	v_add_u32_e32 v118, s85, v229
	v_add_u32_e32 v150, s89, v229
	ds_read_b128 v[106:109], v118
	ds_read_b128 v[110:113], v118 offset:1024
	ds_read_b128 v[114:117], v118 offset:2048
	ds_read_b128 v[118:121], v118 offset:3072
	ds_read_b128 v[122:125], v150
	ds_read_b128 v[126:129], v150 offset:1024
	ds_read_b128 v[142:145], v150 offset:2048
	ds_read_b128 v[150:153], v150 offset:3072
	v_lshl_add_u64 v[194:195], s[4:5], 0, v[218:219]
	s_add_i32 m0, s35, 0xc000
	ds_read_b128 v[162:165], v230
	ds_read_b128 v[166:169], v230 offset:1024
	ds_read_b128 v[170:173], v230 offset:2048
	ds_read_b128 v[174:177], v230 offset:3072
	ds_read_b128 v[178:181], v230 offset:4096
	ds_read_b128 v[182:185], v230 offset:5120
	ds_read_b128 v[186:189], v230 offset:6144
	ds_read_b128 v[190:193], v230 offset:7168
	global_load_lds_dwordx4 v[194:195], off
	v_lshl_add_u64 v[194:195], s[4:5], 0, v[220:221]
	s_add_i32 m0, s35, 0xe000
	s_nop 0
	global_load_lds_dwordx4 v[194:195], off
	s_waitcnt vmcnt(8)
	s_waitcnt lgkmcnt(0)
	s_barrier
	s_setprio 1
	s_waitcnt lgkmcnt(0)
	v_mfma_f32_16x16x32_bf16 v[158:161], v[106:109], v[162:165], 0
	v_mfma_f32_16x16x32_bf16 v[154:157], v[114:117], v[162:165], 0
	v_mfma_f32_16x16x32_bf16 v[134:137], v[106:109], v[170:173], 0
	v_mfma_f32_16x16x32_bf16 v[130:133], v[114:117], v[170:173], 0
	v_mfma_f32_16x16x32_bf16 v[94:97], v[106:109], v[178:181], 0
	v_mfma_f32_16x16x32_bf16 v[90:93], v[114:117], v[178:181], 0
	v_mfma_f32_16x16x32_bf16 v[78:81], v[106:109], v[186:189], 0
	v_mfma_f32_16x16x32_bf16 v[74:77], v[114:117], v[186:189], 0
	v_mfma_f32_16x16x32_bf16 v[158:161], v[110:113], v[166:169], v[158:161]
	v_mfma_f32_16x16x32_bf16 v[154:157], v[118:121], v[166:169], v[154:157]
	v_mfma_f32_16x16x32_bf16 v[134:137], v[110:113], v[174:177], v[134:137]
	v_mfma_f32_16x16x32_bf16 v[130:133], v[118:121], v[174:177], v[130:133]
	v_mfma_f32_16x16x32_bf16 v[94:97], v[110:113], v[182:185], v[94:97]
	v_mfma_f32_16x16x32_bf16 v[90:93], v[118:121], v[182:185], v[90:93]
	v_mfma_f32_16x16x32_bf16 v[78:81], v[110:113], v[190:193], v[78:81]
	v_mfma_f32_16x16x32_bf16 v[74:77], v[118:121], v[190:193], v[74:77]
	s_setprio 0
	s_setprio 1
	v_mfma_f32_16x16x32_bf16 v[146:149], v[122:125], v[162:165], 0
	v_mfma_f32_16x16x32_bf16 v[138:141], v[142:145], v[162:165], 0
	v_mfma_f32_16x16x32_bf16 v[102:105], v[122:125], v[170:173], 0
	v_mfma_f32_16x16x32_bf16 v[98:101], v[142:145], v[170:173], 0
	v_mfma_f32_16x16x32_bf16 v[86:89], v[122:125], v[178:181], 0
	v_mfma_f32_16x16x32_bf16 v[82:85], v[142:145], v[178:181], 0
	v_mfma_f32_16x16x32_bf16 v[70:73], v[122:125], v[186:189], 0
	v_mfma_f32_16x16x32_bf16 v[66:69], v[142:145], v[186:189], 0
	v_mfma_f32_16x16x32_bf16 v[146:149], v[126:129], v[166:169], v[146:149]
	v_mfma_f32_16x16x32_bf16 v[138:141], v[150:153], v[166:169], v[138:141]
	v_mfma_f32_16x16x32_bf16 v[102:105], v[126:129], v[174:177], v[102:105]
	v_mfma_f32_16x16x32_bf16 v[98:101], v[150:153], v[174:177], v[98:101]
	v_mfma_f32_16x16x32_bf16 v[86:89], v[126:129], v[182:185], v[86:89]
	v_mfma_f32_16x16x32_bf16 v[82:85], v[150:153], v[182:185], v[82:85]
	v_mfma_f32_16x16x32_bf16 v[70:73], v[126:129], v[190:193], v[70:73]
	v_mfma_f32_16x16x32_bf16 v[66:69], v[150:153], v[190:193], v[66:69]
	s_setprio 0
	s_barrier
	s_add_i32 s85, s85, s34
	v_lshl_add_u64 v[194:195], s[30:31], 0, v[214:215]
	s_mov_b32 m0, s85
	ds_read_b128 v[162:165], v230 offset:16384
	ds_read_b128 v[166:169], v230 offset:17408
	ds_read_b128 v[170:173], v230 offset:18432
	ds_read_b128 v[174:177], v230 offset:19456
	ds_read_b128 v[178:181], v230 offset:20480
	ds_read_b128 v[182:185], v230 offset:21504
	ds_read_b128 v[186:189], v230 offset:22528
	ds_read_b128 v[190:193], v230 offset:23552
	global_load_lds_dwordx4 v[194:195], off
	s_add_i32 m0, s85, 0x2000
	s_add_u32 s94, s30, 0x20000
	v_lshl_add_u64 v[196:197], s[30:31], 0, v[210:211]
	s_addc_u32 s95, s31, 0
	s_add_i32 s85, s89, s34
	global_load_lds_dwordx4 v[196:197], off
	v_lshl_add_u64 v[198:199], s[94:95], 0, v[214:215]
	s_mov_b32 m0, s85
	v_lshl_add_u64 v[200:201], s[40:41], 0, v[212:213]
	global_load_lds_dwordx4 v[198:199], off
	v_lshl_add_u64 v[198:199], s[94:95], 0, v[210:211]
	s_add_i32 m0, s85, 0x2000
	s_nop 0
	global_load_lds_dwordx4 v[198:199], off
	v_lshl_add_u64 v[198:199], s[40:41], 0, v[216:217]
	s_mov_b32 m0, s35
	s_nop 0
	global_load_lds_dwordx4 v[198:199], off
	s_mov_b32 m0, s36
	s_nop 0
	global_load_lds_dwordx4 v[200:201], off
	s_waitcnt vmcnt(8)
	s_waitcnt lgkmcnt(0)
	s_barrier
; #define PG8_STAGE(bufoff, gbase, voff) do { _Pragma("unroll") for (int _i = 0; _i < 2; ++_i) \
;         __builtin_amdgcn_global_load_lds((const unsigned*)((const char*)(gbase) + (voff)[_i]), (PG8_LAS unsigned*)(lds + (bufoff) + ldsw + _i * 8192), 16, 0, 0); } while (0)
; #define PG8_LDA(dst, b, h) do { _Pragma("unroll") for (int m = 0; m < 4; ++m) _Pragma("unroll") for (int k = 0; k < 2; ++k) dst[m][k] = *(const PG8_LAS bf16x8*)(lds + PG8_SA(b, h) + aoff + m * 2048 + k * 1024); } while (0)
; #define PG8_LDB(dst, b, h) do { _Pragma("unroll") for (int n = 0; n < 2; ++n) _Pragma("unroll") for (int k = 0; k < 2; ++k) dst[n][k] = *(const PG8_LAS bf16x8*)(lds + PG8_SB(b, h) + boff + n * 2048 + k * 1024); } while (0)
; #define PG8_MMA(ai, bj, At, Bt) do { __builtin_amdgcn_s_setprio(1); _Pragma("unroll") for (int m = 0; m < 4; ++m) _Pragma("unroll") for (int n = 0; n < 2; ++n) _Pragma("unroll") for (int k = 0; k < 2; ++k) \
;         acc[ai][bj][m][n] = __builtin_amdgcn_mfma_f32_16x16x32_bf16(Bt[n][k], At[m][k], acc[ai][bj][m][n], 0, 0, 0); __builtin_amdgcn_s_setprio(0); } while (0)
; #define PG8_WAIT_V(n) asm volatile("s_waitcnt vmcnt(" #n ")" ::: "memory")
; #define PG8_WAIT_L(n) asm volatile("s_waitcnt lgkmcnt(" #n ")" ::: "memory")
; #define PG8_BAR __builtin_amdgcn_s_barrier()
; #define PG8_SCHED __builtin_amdgcn_sched_barrier(0)
; template <class Epi, class Sched, bool ALIGN_EPI = false, bool SP2 = false>
; __device__ __forceinline__ void gemm_phase(PG8_LAS unsigned char* lds, const Gemm g, const Sched& S, const Epi& E, int wave_s) {
;     ...
;             PG8_WAIT_V(8); PG8_WAIT_L(0); PG8_BAR; PG8_MMA(1, 0, At, B0); PG8_MMA(1, 1, At, B1); PG8_BAR; PG8_SCHED;
;             PG8_LDB(B0, 1, 0); PG8_LDB(B1, 1, 1); PG8_SCHED; PG8_LDA(At, 1, 0); PG8_STAGE(PG8_SA(0, 1), a2 + hstepA, voffA);
;             PG8_WAIT_V(8); PG8_WAIT_L(0); PG8_BAR; PG8_MMA(0, 0, At, B0); PG8_MMA(0, 1, At, B1); PG8_BAR; PG8_SCHED;
	s_setprio 1
	s_waitcnt lgkmcnt(0)
	v_mfma_f32_16x16x32_bf16 v[62:65], v[106:109], v[162:165], 0
	v_mfma_f32_16x16x32_bf16 v[58:61], v[114:117], v[162:165], 0
	v_mfma_f32_16x16x32_bf16 v[46:49], v[106:109], v[170:173], 0
	v_mfma_f32_16x16x32_bf16 v[42:45], v[114:117], v[170:173], 0
	v_mfma_f32_16x16x32_bf16 v[30:33], v[106:109], v[178:181], 0
	v_mfma_f32_16x16x32_bf16 v[26:29], v[114:117], v[178:181], 0
	v_mfma_f32_16x16x32_bf16 v[14:17], v[106:109], v[186:189], 0
	v_mfma_f32_16x16x32_bf16 v[10:13], v[114:117], v[186:189], 0
	v_mfma_f32_16x16x32_bf16 v[62:65], v[110:113], v[166:169], v[62:65]
	v_mfma_f32_16x16x32_bf16 v[58:61], v[118:121], v[166:169], v[58:61]
	v_mfma_f32_16x16x32_bf16 v[46:49], v[110:113], v[174:177], v[46:49]
	v_mfma_f32_16x16x32_bf16 v[42:45], v[118:121], v[174:177], v[42:45]
	v_mfma_f32_16x16x32_bf16 v[30:33], v[110:113], v[182:185], v[30:33]
	v_mfma_f32_16x16x32_bf16 v[26:29], v[118:121], v[182:185], v[26:29]
	v_mfma_f32_16x16x32_bf16 v[14:17], v[110:113], v[190:193], v[14:17]
	v_mfma_f32_16x16x32_bf16 v[10:13], v[118:121], v[190:193], v[10:13]
	s_setprio 0
	s_setprio 1
	v_mfma_f32_16x16x32_bf16 v[54:57], v[122:125], v[162:165], 0
	v_mfma_f32_16x16x32_bf16 v[50:53], v[142:145], v[162:165], 0
	v_mfma_f32_16x16x32_bf16 v[38:41], v[122:125], v[170:173], 0
	v_mfma_f32_16x16x32_bf16 v[34:37], v[142:145], v[170:173], 0
	v_mfma_f32_16x16x32_bf16 v[22:25], v[122:125], v[178:181], 0
	v_mfma_f32_16x16x32_bf16 v[18:21], v[142:145], v[178:181], 0
	v_mfma_f32_16x16x32_bf16 v[6:9], v[122:125], v[186:189], 0
	v_mfma_f32_16x16x32_bf16 v[2:5], v[142:145], v[186:189], 0
	v_mfma_f32_16x16x32_bf16 v[54:57], v[126:129], v[166:169], v[54:57]
	v_mfma_f32_16x16x32_bf16 v[50:53], v[150:153], v[166:169], v[50:53]
	v_mfma_f32_16x16x32_bf16 v[38:41], v[126:129], v[174:177], v[38:41]
	v_mfma_f32_16x16x32_bf16 v[34:37], v[150:153], v[174:177], v[34:37]
	v_mfma_f32_16x16x32_bf16 v[22:25], v[126:129], v[182:185], v[22:25]
	v_mfma_f32_16x16x32_bf16 v[18:21], v[150:153], v[182:185], v[18:21]
	v_mfma_f32_16x16x32_bf16 v[6:9], v[126:129], v[190:193], v[6:9]
	v_mfma_f32_16x16x32_bf16 v[2:5], v[150:153], v[190:193], v[2:5]
	s_setprio 0
	s_barrier
	s_add_i32 s85, 0, 0x18000
	s_add_i32 s89, 0, 0x1c000
	v_add_u32_e32 v118, s85, v229
	v_add_u32_e32 v150, s89, v229
	ds_read_b128 v[106:109], v118
	ds_read_b128 v[110:113], v118 offset:1024
	ds_read_b128 v[114:117], v118 offset:2048
	ds_read_b128 v[118:121], v118 offset:3072
	ds_read_b128 v[122:125], v150
	ds_read_b128 v[126:129], v150 offset:1024
	ds_read_b128 v[142:145], v150 offset:2048
	ds_read_b128 v[150:153], v150 offset:3072
	s_add_u32 s40, s40, 0x80000
	s_addc_u32 s41, s41, 0
	s_mov_b32 m0, s37
	v_lshl_add_u64 v[202:203], s[40:41], 0, v[216:217]
	ds_read_b128 v[162:165], v230 offset:32768
	ds_read_b128 v[166:169], v230 offset:33792
	ds_read_b128 v[170:173], v230 offset:34816
	ds_read_b128 v[174:177], v230 offset:35840
	ds_read_b128 v[178:181], v230 offset:36864
	ds_read_b128 v[182:185], v230 offset:37888
	ds_read_b128 v[186:189], v230 offset:38912
	ds_read_b128 v[190:193], v230 offset:39936
	global_load_lds_dwordx4 v[202:203], off
	v_lshl_add_u64 v[202:203], s[40:41], 0, v[212:213]
	s_mov_b32 m0, s42
	s_nop 0
	global_load_lds_dwordx4 v[202:203], off
	s_waitcnt vmcnt(8)
	s_waitcnt lgkmcnt(0)
	s_barrier
	s_setprio 1
	s_waitcnt lgkmcnt(0)
	v_mfma_f32_16x16x32_bf16 v[158:161], v[106:109], v[162:165], v[158:161]
	v_mfma_f32_16x16x32_bf16 v[154:157], v[114:117], v[162:165], v[154:157]
	v_mfma_f32_16x16x32_bf16 v[134:137], v[106:109], v[170:173], v[134:137]
	v_mfma_f32_16x16x32_bf16 v[130:133], v[114:117], v[170:173], v[130:133]
	v_mfma_f32_16x16x32_bf16 v[94:97], v[106:109], v[178:181], v[94:97]
	v_mfma_f32_16x16x32_bf16 v[90:93], v[114:117], v[178:181], v[90:93]
	v_mfma_f32_16x16x32_bf16 v[78:81], v[106:109], v[186:189], v[78:81]
	v_mfma_f32_16x16x32_bf16 v[74:77], v[114:117], v[186:189], v[74:77]
	v_mfma_f32_16x16x32_bf16 v[158:161], v[110:113], v[166:169], v[158:161]
	v_mfma_f32_16x16x32_bf16 v[154:157], v[118:121], v[166:169], v[154:157]
	v_mfma_f32_16x16x32_bf16 v[134:137], v[110:113], v[174:177], v[134:137]
	v_mfma_f32_16x16x32_bf16 v[130:133], v[118:121], v[174:177], v[130:133]
	v_mfma_f32_16x16x32_bf16 v[94:97], v[110:113], v[182:185], v[94:97]
	v_mfma_f32_16x16x32_bf16 v[90:93], v[118:121], v[182:185], v[90:93]
	v_mfma_f32_16x16x32_bf16 v[78:81], v[110:113], v[190:193], v[78:81]
	v_mfma_f32_16x16x32_bf16 v[74:77], v[118:121], v[190:193], v[74:77]
	s_setprio 0
	s_setprio 1
	v_mfma_f32_16x16x32_bf16 v[146:149], v[122:125], v[162:165], v[146:149]
	v_mfma_f32_16x16x32_bf16 v[138:141], v[142:145], v[162:165], v[138:141]
	v_mfma_f32_16x16x32_bf16 v[102:105], v[122:125], v[170:173], v[102:105]
	v_mfma_f32_16x16x32_bf16 v[98:101], v[142:145], v[170:173], v[98:101]
	v_mfma_f32_16x16x32_bf16 v[86:89], v[122:125], v[178:181], v[86:89]
	v_mfma_f32_16x16x32_bf16 v[82:85], v[142:145], v[178:181], v[82:85]
	v_mfma_f32_16x16x32_bf16 v[70:73], v[122:125], v[186:189], v[70:73]
	v_mfma_f32_16x16x32_bf16 v[66:69], v[142:145], v[186:189], v[66:69]
	v_mfma_f32_16x16x32_bf16 v[146:149], v[126:129], v[166:169], v[146:149]
	v_mfma_f32_16x16x32_bf16 v[138:141], v[150:153], v[166:169], v[138:141]
	v_mfma_f32_16x16x32_bf16 v[102:105], v[126:129], v[174:177], v[102:105]
	v_mfma_f32_16x16x32_bf16 v[98:101], v[150:153], v[174:177], v[98:101]
	v_mfma_f32_16x16x32_bf16 v[86:89], v[126:129], v[182:185], v[86:89]
	v_mfma_f32_16x16x32_bf16 v[82:85], v[150:153], v[182:185], v[82:85]
	v_mfma_f32_16x16x32_bf16 v[70:73], v[126:129], v[190:193], v[70:73]
	v_mfma_f32_16x16x32_bf16 v[66:69], v[150:153], v[190:193], v[66:69]
	s_setprio 0
	s_barrier
; #define PG8_STAGE(bufoff, gbase, voff) do { _Pragma("unroll") for (int _i = 0; _i < 2; ++_i) \
;         __builtin_amdgcn_global_load_lds((const unsigned*)((const char*)(gbase) + (voff)[_i]), (PG8_LAS unsigned*)(lds + (bufoff) + ldsw + _i * 8192), 16, 0, 0); } while (0)
; #define PG8_LDA(dst, b, h) do { _Pragma("unroll") for (int m = 0; m < 4; ++m) _Pragma("unroll") for (int k = 0; k < 2; ++k) dst[m][k] = *(const PG8_LAS bf16x8*)(lds + PG8_SA(b, h) + aoff + m * 2048 + k * 1024); } while (0)
; #define PG8_MMA(ai, bj, At, Bt) do { __builtin_amdgcn_s_setprio(1); _Pragma("unroll") for (int m = 0; m < 4; ++m) _Pragma("unroll") for (int n = 0; n < 2; ++n) _Pragma("unroll") for (int k = 0; k < 2; ++k) \
;         acc[ai][bj][m][n] = __builtin_amdgcn_mfma_f32_16x16x32_bf16(Bt[n][k], At[m][k], acc[ai][bj][m][n], 0, 0, 0); __builtin_amdgcn_s_setprio(0); } while (0)
; #define PG8_WAIT_V(n) asm volatile("s_waitcnt vmcnt(" #n ")" ::: "memory")
; #define PG8_WAIT_L(n) asm volatile("s_waitcnt lgkmcnt(" #n ")" ::: "memory")
; #define PG8_BAR __builtin_amdgcn_s_barrier()
; #define PG8_SCHED __builtin_amdgcn_sched_barrier(0)
; template <class Epi, class Sched, bool ALIGN_EPI = false, bool SP2 = false>
; __device__ __forceinline__ void gemm_phase(PG8_LAS unsigned char* lds, const Gemm g, const Sched& S, const Epi& E, int wave_s) {
;     ...
;         for (int t = 0; t < nt; t += 2) {
;     ...
;             PG8_LDA(At, 1, 1); PG8_STAGE(PG8_SB(1, 0), b3, voffB); PG8_STAGE(PG8_SB(1, 1), b3 + hstepB, voffB); PG8_STAGE(PG8_SA(1, 0), a3, voffA);
;             PG8_WAIT_V(8); PG8_WAIT_L(0); PG8_BAR; PG8_MMA(1, 0, At, B0); PG8_MMA(1, 1, At, B1); PG8_BAR; PG8_SCHED;
	s_add_i32 s40, s85, s34
	v_lshl_add_u64 v[194:195], v[194:195], 0, s[60:61]
	s_mov_b32 m0, s40
	ds_read_b128 v[162:165], v230 offset:49152
	ds_read_b128 v[166:169], v230 offset:50176
	ds_read_b128 v[170:173], v230 offset:51200
	ds_read_b128 v[174:177], v230 offset:52224
	ds_read_b128 v[178:181], v230 offset:53248
	ds_read_b128 v[182:185], v230 offset:54272
	ds_read_b128 v[186:189], v230 offset:55296
	ds_read_b128 v[190:193], v230 offset:56320
	global_load_lds_dwordx4 v[194:195], off
	s_add_i32 m0, s40, 0x2000
	s_add_u32 s30, s30, 0x20080
	v_lshl_add_u64 v[194:195], v[196:197], 0, s[60:61]
	s_addc_u32 s31, s31, 0
	s_add_i32 s40, s89, s34
	global_load_lds_dwordx4 v[194:195], off
	v_lshl_add_u64 v[194:195], s[30:31], 0, v[214:215]
	s_mov_b32 m0, s40
	s_nop 0
	global_load_lds_dwordx4 v[194:195], off
	v_lshl_add_u64 v[194:195], s[30:31], 0, v[210:211]
	s_add_i32 m0, s40, 0x2000
	s_nop 0
	global_load_lds_dwordx4 v[194:195], off
	v_lshl_add_u64 v[194:195], v[198:199], 0, s[60:61]
	s_mov_b32 m0, s46
	s_nop 0
	global_load_lds_dwordx4 v[194:195], off
	v_lshl_add_u64 v[194:195], v[200:201], 0, s[60:61]
	s_mov_b32 m0, s47
	s_nop 0
	global_load_lds_dwordx4 v[194:195], off
	s_waitcnt vmcnt(8)
	s_waitcnt lgkmcnt(0)
	s_barrier
	s_setprio 1
	s_waitcnt lgkmcnt(0)
	v_mfma_f32_16x16x32_bf16 v[62:65], v[106:109], v[162:165], v[62:65]
	v_mfma_f32_16x16x32_bf16 v[58:61], v[114:117], v[162:165], v[58:61]
	v_mfma_f32_16x16x32_bf16 v[46:49], v[106:109], v[170:173], v[46:49]
	v_mfma_f32_16x16x32_bf16 v[42:45], v[114:117], v[170:173], v[42:45]
	v_mfma_f32_16x16x32_bf16 v[30:33], v[106:109], v[178:181], v[30:33]
	v_mfma_f32_16x16x32_bf16 v[26:29], v[114:117], v[178:181], v[26:29]
	v_mfma_f32_16x16x32_bf16 v[14:17], v[106:109], v[186:189], v[14:17]
	v_mfma_f32_16x16x32_bf16 v[10:13], v[114:117], v[186:189], v[10:13]
	v_mfma_f32_16x16x32_bf16 v[62:65], v[110:113], v[166:169], v[62:65]
	v_mfma_f32_16x16x32_bf16 v[58:61], v[118:121], v[166:169], v[58:61]
	v_mfma_f32_16x16x32_bf16 v[46:49], v[110:113], v[174:177], v[46:49]
	v_mfma_f32_16x16x32_bf16 v[42:45], v[118:121], v[174:177], v[42:45]
	v_mfma_f32_16x16x32_bf16 v[30:33], v[110:113], v[182:185], v[30:33]
	v_mfma_f32_16x16x32_bf16 v[26:29], v[118:121], v[182:185], v[26:29]
	v_mfma_f32_16x16x32_bf16 v[14:17], v[110:113], v[190:193], v[14:17]
	v_mfma_f32_16x16x32_bf16 v[10:13], v[118:121], v[190:193], v[10:13]
	s_setprio 0
	s_setprio 1
	v_mfma_f32_16x16x32_bf16 v[54:57], v[122:125], v[162:165], v[54:57]
	v_mfma_f32_16x16x32_bf16 v[50:53], v[142:145], v[162:165], v[50:53]
	v_mfma_f32_16x16x32_bf16 v[38:41], v[122:125], v[170:173], v[38:41]
	v_mfma_f32_16x16x32_bf16 v[34:37], v[142:145], v[170:173], v[34:37]
	v_mfma_f32_16x16x32_bf16 v[22:25], v[122:125], v[178:181], v[22:25]
	v_mfma_f32_16x16x32_bf16 v[18:21], v[142:145], v[178:181], v[18:21]
	v_mfma_f32_16x16x32_bf16 v[6:9], v[122:125], v[186:189], v[6:9]
	v_mfma_f32_16x16x32_bf16 v[2:5], v[142:145], v[186:189], v[2:5]
	v_mfma_f32_16x16x32_bf16 v[54:57], v[126:129], v[166:169], v[54:57]
	v_mfma_f32_16x16x32_bf16 v[50:53], v[150:153], v[166:169], v[50:53]
	v_mfma_f32_16x16x32_bf16 v[38:41], v[126:129], v[174:177], v[38:41]
	v_mfma_f32_16x16x32_bf16 v[34:37], v[150:153], v[174:177], v[34:37]
	v_mfma_f32_16x16x32_bf16 v[22:25], v[126:129], v[182:185], v[22:25]
	v_mfma_f32_16x16x32_bf16 v[18:21], v[150:153], v[182:185], v[18:21]
	v_mfma_f32_16x16x32_bf16 v[6:9], v[126:129], v[190:193], v[6:9]
	v_mfma_f32_16x16x32_bf16 v[2:5], v[150:153], v[190:193], v[2:5]
	s_setprio 0
	s_barrier
	s_add_i32 s84, s84, 2
	s_add_u32 s4, s4, 0x100
	s_addc_u32 s5, s5, 0
	s_add_u32 s29, s29, 0x100
	s_addc_u32 s81, s81, 0
	s_cmp_gt_u32 s84, 5

; #define PG8_STAGE(bufoff, gbase, voff) do { _Pragma("unroll") for (int _i = 0; _i < 2; ++_i) \
;         __builtin_amdgcn_global_load_lds((const unsigned*)((const char*)(gbase) + (voff)[_i]), (PG8_LAS unsigned*)(lds + (bufoff) + ldsw + _i * 8192), 16, 0, 0); } while (0)
; #define PG8_LDA(dst, b, h) do { _Pragma("unroll") for (int m = 0; m < 4; ++m) _Pragma("unroll") for (int k = 0; k < 2; ++k) dst[m][k] = *(const PG8_LAS bf16x8*)(lds + PG8_SA(b, h) + aoff + m * 2048 + k * 1024); } while (0)
; #define PG8_LDB(dst, b, h) do { _Pragma("unroll") for (int n = 0; n < 2; ++n) _Pragma("unroll") for (int k = 0; k < 2; ++k) dst[n][k] = *(const PG8_LAS bf16x8*)(lds + PG8_SB(b, h) + boff + n * 2048 + k * 1024); } while (0)
; #define PG8_MMA(ai, bj, At, Bt) do { __builtin_amdgcn_s_setprio(1); _Pragma("unroll") for (int m = 0; m < 4; ++m) _Pragma("unroll") for (int n = 0; n < 2; ++n) _Pragma("unroll") for (int k = 0; k < 2; ++k) \
;         acc[ai][bj][m][n] = __builtin_amdgcn_mfma_f32_16x16x32_bf16(Bt[n][k], At[m][k], acc[ai][bj][m][n], 0, 0, 0); __builtin_amdgcn_s_setprio(0); } while (0)
; #define PG8_WAIT_V(n) asm volatile("s_waitcnt vmcnt(" #n ")" ::: "memory")
; #define PG8_WAIT_L(n) asm volatile("s_waitcnt lgkmcnt(" #n ")" ::: "memory")
; #define PG8_BAR __builtin_amdgcn_s_barrier()
; #define PG8_SCHED __builtin_amdgcn_sched_barrier(0)
; template <class Epi, class Sched, bool ALIGN_EPI = false, bool SP2 = false>
; __device__ __forceinline__ void gemm_phase(PG8_LAS unsigned char* lds, const Gemm g, const Sched& S, const Epi& E, int wave_s) {
;     ...
;             PG8_LDB(B0, 0, 0); PG8_LDB(B1, 0, 1); PG8_SCHED; PG8_LDA(At, 0, 0); PG8_STAGE(PG8_SA(1, 1), a1 + hstepA, voffA);
;             PG8_WAIT_V(8); PG8_WAIT_L(0); PG8_BAR; PG8_MMA(0, 0, At, B0); PG8_MMA(0, 1, At, B1); PG8_BAR; PG8_SCHED;
;             PG8_LDA(At, 0, 1); PG8_STAGE(PG8_SB(0, 0), b2, voffB); PG8_STAGE(PG8_SB(0, 1), b2 + hstepB, voffB); PG8_STAGE(PG8_SA(0, 0), a2, voffA);
;             PG8_WAIT_V(8); PG8_WAIT_L(0); PG8_BAR; PG8_MMA(1, 0, At, B0); PG8_MMA(1, 1, At, B1); PG8_BAR; PG8_SCHED;
.LBB0_411:
	s_ashr_i32 s15, s14, 31
	s_lshl_b64 s[2:3], s[14:15], 20
	s_add_u32 s28, s22, s2
	s_addc_u32 s29, s23, s3
	s_and_b64 s[2:3], s[4:5], exec
	s_cselect_b32 s2, s29, s31
	s_cselect_b32 s3, s28, s30
	s_add_u32 s4, s40, 0x80080
	s_addc_u32 s5, s41, 0
	s_add_u32 s15, s30, 0x100
	s_addc_u32 s21, s31, 0
	s_mov_b32 s94, -2
	s_add_u32 s30, s4, 0xfff80080
	s_addc_u32 s31, s5, -1
	s_add_i32 s95, 0, 0x10000
	s_cmp_eq_u32 s94, 28
	s_cselect_b32 s41, s27, s31
	s_cselect_b32 s40, s26, s30
	v_add_u32_e32 v149, s95, v147
	s_cselect_b32 s31, s2, s21
	s_cselect_b32 s30, s3, s15
	s_add_i32 vcc_lo, 0, 0x14000
	ds_read_b128 v[142:145], v149
	ds_read_b128 v[150:153], v149 offset:1024
	ds_read_b128 v[154:157], v149 offset:2048
	ds_read_b128 v[158:161], v149 offset:3072
	v_add_u32_e32 v149, vcc_lo, v147
	ds_read_b128 v[162:165], v149
	ds_read_b128 v[166:169], v149 offset:1024
	ds_read_b128 v[170:173], v149 offset:2048
	ds_read_b128 v[174:177], v149 offset:3072
	v_lshl_add_u64 v[210:211], s[4:5], 0, v[138:139]
	s_add_i32 m0, s35, 0xc000
	ds_read_b128 v[178:181], v148
	ds_read_b128 v[182:185], v148 offset:1024
	ds_read_b128 v[186:189], v148 offset:2048
	ds_read_b128 v[190:193], v148 offset:3072
	ds_read_b128 v[194:197], v148 offset:4096
	ds_read_b128 v[198:201], v148 offset:5120
	ds_read_b128 v[202:205], v148 offset:6144
	ds_read_b128 v[206:209], v148 offset:7168
	global_load_lds_dwordx4 v[210:211], off
	v_lshl_add_u64 v[210:211], s[4:5], 0, v[140:141]
	s_add_i32 m0, s35, 0xe000
	s_nop 0
	global_load_lds_dwordx4 v[210:211], off
	s_waitcnt vmcnt(8)
	s_waitcnt lgkmcnt(0)
	s_barrier
	s_setprio 1
	s_waitcnt lgkmcnt(0)
	v_mfma_f32_16x16x32_bf16 v[126:129], v[142:145], v[178:181], 0
	v_mfma_f32_16x16x32_bf16 v[122:125], v[154:157], v[178:181], 0
	v_mfma_f32_16x16x32_bf16 v[110:113], v[142:145], v[186:189], 0
	v_mfma_f32_16x16x32_bf16 v[106:109], v[154:157], v[186:189], 0
	v_mfma_f32_16x16x32_bf16 v[94:97], v[142:145], v[194:197], 0
	v_mfma_f32_16x16x32_bf16 v[90:93], v[154:157], v[194:197], 0
	v_mfma_f32_16x16x32_bf16 v[78:81], v[142:145], v[202:205], 0
	v_mfma_f32_16x16x32_bf16 v[74:77], v[154:157], v[202:205], 0
	v_mfma_f32_16x16x32_bf16 v[126:129], v[150:153], v[182:185], v[126:129]
	v_mfma_f32_16x16x32_bf16 v[122:125], v[158:161], v[182:185], v[122:125]
	v_mfma_f32_16x16x32_bf16 v[110:113], v[150:153], v[190:193], v[110:113]
	v_mfma_f32_16x16x32_bf16 v[106:109], v[158:161], v[190:193], v[106:109]
	v_mfma_f32_16x16x32_bf16 v[94:97], v[150:153], v[198:201], v[94:97]
	v_mfma_f32_16x16x32_bf16 v[90:93], v[158:161], v[198:201], v[90:93]
	v_mfma_f32_16x16x32_bf16 v[78:81], v[150:153], v[206:209], v[78:81]
	v_mfma_f32_16x16x32_bf16 v[74:77], v[158:161], v[206:209], v[74:77]
	s_setprio 0
	s_setprio 1
	v_mfma_f32_16x16x32_bf16 v[118:121], v[162:165], v[178:181], 0
	v_mfma_f32_16x16x32_bf16 v[114:117], v[170:173], v[178:181], 0
	v_mfma_f32_16x16x32_bf16 v[102:105], v[162:165], v[186:189], 0
	v_mfma_f32_16x16x32_bf16 v[98:101], v[170:173], v[186:189], 0
	v_mfma_f32_16x16x32_bf16 v[86:89], v[162:165], v[194:197], 0
	v_mfma_f32_16x16x32_bf16 v[82:85], v[170:173], v[194:197], 0
	v_mfma_f32_16x16x32_bf16 v[70:73], v[162:165], v[202:205], 0
	v_mfma_f32_16x16x32_bf16 v[66:69], v[170:173], v[202:205], 0
	v_mfma_f32_16x16x32_bf16 v[118:121], v[166:169], v[182:185], v[118:121]
	v_mfma_f32_16x16x32_bf16 v[114:117], v[174:177], v[182:185], v[114:117]
	v_mfma_f32_16x16x32_bf16 v[102:105], v[166:169], v[190:193], v[102:105]
	v_mfma_f32_16x16x32_bf16 v[98:101], v[174:177], v[190:193], v[98:101]
	v_mfma_f32_16x16x32_bf16 v[86:89], v[166:169], v[198:201], v[86:89]
	v_mfma_f32_16x16x32_bf16 v[82:85], v[174:177], v[198:201], v[82:85]
	v_mfma_f32_16x16x32_bf16 v[70:73], v[166:169], v[206:209], v[70:73]
	v_mfma_f32_16x16x32_bf16 v[66:69], v[174:177], v[206:209], v[66:69]
	s_setprio 0
	s_barrier
	s_add_i32 s95, s95, s34
	v_lshl_add_u64 v[210:211], s[30:31], 0, v[132:133]
	s_mov_b32 m0, s95
	ds_read_b128 v[178:181], v148 offset:16384
	ds_read_b128 v[182:185], v148 offset:17408
	ds_read_b128 v[186:189], v148 offset:18432
	ds_read_b128 v[190:193], v148 offset:19456
	ds_read_b128 v[194:197], v148 offset:20480
	ds_read_b128 v[198:201], v148 offset:21504
	ds_read_b128 v[202:205], v148 offset:22528
	ds_read_b128 v[206:209], v148 offset:23552
	global_load_lds_dwordx4 v[210:211], off
	s_add_i32 m0, s95, 0x2000
	s_add_u32 s96, s30, 0x80000
	v_lshl_add_u64 v[212:213], s[30:31], 0, v[136:137]
	s_addc_u32 s97, s31, 0
	s_add_i32 s95, vcc_lo, s34
	global_load_lds_dwordx4 v[212:213], off
	v_lshl_add_u64 v[214:215], s[96:97], 0, v[132:133]
	s_mov_b32 m0, s95
	v_lshl_add_u64 v[216:217], s[40:41], 0, v[134:135]
	global_load_lds_dwordx4 v[214:215], off
	v_lshl_add_u64 v[214:215], s[96:97], 0, v[136:137]
	s_add_i32 m0, s95, 0x2000
	s_nop 0
	global_load_lds_dwordx4 v[214:215], off
	v_lshl_add_u64 v[214:215], s[40:41], 0, v[130:131]
	s_mov_b32 m0, s35
	s_nop 0
	global_load_lds_dwordx4 v[214:215], off
	s_mov_b32 m0, s36
	s_nop 0
	global_load_lds_dwordx4 v[216:217], off
	s_waitcnt vmcnt(8)
	s_waitcnt lgkmcnt(0)
	s_barrier
; #define PG8_STAGE(bufoff, gbase, voff) do { _Pragma("unroll") for (int _i = 0; _i < 2; ++_i) \
;         __builtin_amdgcn_global_load_lds((const unsigned*)((const char*)(gbase) + (voff)[_i]), (PG8_LAS unsigned*)(lds + (bufoff) + ldsw + _i * 8192), 16, 0, 0); } while (0)
; #define PG8_LDA(dst, b, h) do { _Pragma("unroll") for (int m = 0; m < 4; ++m) _Pragma("unroll") for (int k = 0; k < 2; ++k) dst[m][k] = *(const PG8_LAS bf16x8*)(lds + PG8_SA(b, h) + aoff + m * 2048 + k * 1024); } while (0)
; #define PG8_LDB(dst, b, h) do { _Pragma("unroll") for (int n = 0; n < 2; ++n) _Pragma("unroll") for (int k = 0; k < 2; ++k) dst[n][k] = *(const PG8_LAS bf16x8*)(lds + PG8_SB(b, h) + boff + n * 2048 + k * 1024); } while (0)
; #define PG8_MMA(ai, bj, At, Bt) do { __builtin_amdgcn_s_setprio(1); _Pragma("unroll") for (int m = 0; m < 4; ++m) _Pragma("unroll") for (int n = 0; n < 2; ++n) _Pragma("unroll") for (int k = 0; k < 2; ++k) \
;         acc[ai][bj][m][n] = __builtin_amdgcn_mfma_f32_16x16x32_bf16(Bt[n][k], At[m][k], acc[ai][bj][m][n], 0, 0, 0); __builtin_amdgcn_s_setprio(0); } while (0)
; #define PG8_WAIT_V(n) asm volatile("s_waitcnt vmcnt(" #n ")" ::: "memory")
; #define PG8_WAIT_L(n) asm volatile("s_waitcnt lgkmcnt(" #n ")" ::: "memory")
; #define PG8_BAR __builtin_amdgcn_s_barrier()
; #define PG8_SCHED __builtin_amdgcn_sched_barrier(0)
; template <class Epi, class Sched, bool ALIGN_EPI = false, bool SP2 = false>
; __device__ __forceinline__ void gemm_phase(PG8_LAS unsigned char* lds, const Gemm g, const Sched& S, const Epi& E, int wave_s) {
;     ...
;             PG8_WAIT_V(8); PG8_WAIT_L(0); PG8_BAR; PG8_MMA(1, 0, At, B0); PG8_MMA(1, 1, At, B1); PG8_BAR; PG8_SCHED;
;             PG8_LDB(B0, 1, 0); PG8_LDB(B1, 1, 1); PG8_SCHED; PG8_LDA(At, 1, 0); PG8_STAGE(PG8_SA(0, 1), a2 + hstepA, voffA);
;             PG8_WAIT_V(8); PG8_WAIT_L(0); PG8_BAR; PG8_MMA(0, 0, At, B0); PG8_MMA(0, 1, At, B1); PG8_BAR; PG8_SCHED;
	s_setprio 1
	s_waitcnt lgkmcnt(0)
	v_mfma_f32_16x16x32_bf16 v[62:65], v[142:145], v[178:181], 0
	v_mfma_f32_16x16x32_bf16 v[58:61], v[154:157], v[178:181], 0
	v_mfma_f32_16x16x32_bf16 v[46:49], v[142:145], v[186:189], 0
	v_mfma_f32_16x16x32_bf16 v[42:45], v[154:157], v[186:189], 0
	v_mfma_f32_16x16x32_bf16 v[30:33], v[142:145], v[194:197], 0
	v_mfma_f32_16x16x32_bf16 v[26:29], v[154:157], v[194:197], 0
	v_mfma_f32_16x16x32_bf16 v[14:17], v[142:145], v[202:205], 0
	v_mfma_f32_16x16x32_bf16 v[10:13], v[154:157], v[202:205], 0
	v_mfma_f32_16x16x32_bf16 v[62:65], v[150:153], v[182:185], v[62:65]
	v_mfma_f32_16x16x32_bf16 v[58:61], v[158:161], v[182:185], v[58:61]
	v_mfma_f32_16x16x32_bf16 v[46:49], v[150:153], v[190:193], v[46:49]
	v_mfma_f32_16x16x32_bf16 v[42:45], v[158:161], v[190:193], v[42:45]
	v_mfma_f32_16x16x32_bf16 v[30:33], v[150:153], v[198:201], v[30:33]
	v_mfma_f32_16x16x32_bf16 v[26:29], v[158:161], v[198:201], v[26:29]
	v_mfma_f32_16x16x32_bf16 v[14:17], v[150:153], v[206:209], v[14:17]
	v_mfma_f32_16x16x32_bf16 v[10:13], v[158:161], v[206:209], v[10:13]
	s_setprio 0
	s_setprio 1
	v_mfma_f32_16x16x32_bf16 v[54:57], v[162:165], v[178:181], 0
	v_mfma_f32_16x16x32_bf16 v[50:53], v[170:173], v[178:181], 0
	v_mfma_f32_16x16x32_bf16 v[38:41], v[162:165], v[186:189], 0
	v_mfma_f32_16x16x32_bf16 v[34:37], v[170:173], v[186:189], 0
	v_mfma_f32_16x16x32_bf16 v[22:25], v[162:165], v[194:197], 0
	v_mfma_f32_16x16x32_bf16 v[18:21], v[170:173], v[194:197], 0
	v_mfma_f32_16x16x32_bf16 v[6:9], v[162:165], v[202:205], 0
	v_mfma_f32_16x16x32_bf16 v[2:5], v[170:173], v[202:205], 0
	v_mfma_f32_16x16x32_bf16 v[54:57], v[166:169], v[182:185], v[54:57]
	v_mfma_f32_16x16x32_bf16 v[50:53], v[174:177], v[182:185], v[50:53]
	v_mfma_f32_16x16x32_bf16 v[38:41], v[166:169], v[190:193], v[38:41]
	v_mfma_f32_16x16x32_bf16 v[34:37], v[174:177], v[190:193], v[34:37]
	v_mfma_f32_16x16x32_bf16 v[22:25], v[166:169], v[198:201], v[22:25]
	v_mfma_f32_16x16x32_bf16 v[18:21], v[174:177], v[198:201], v[18:21]
	v_mfma_f32_16x16x32_bf16 v[6:9], v[166:169], v[206:209], v[6:9]
	v_mfma_f32_16x16x32_bf16 v[2:5], v[174:177], v[206:209], v[2:5]
	s_setprio 0
	s_barrier
	s_add_i32 s95, 0, 0x18000
	v_add_u32_e32 v149, s95, v147
	s_add_i32 s96, 0, 0x1c000
	ds_read_b128 v[142:145], v149
	ds_read_b128 v[150:153], v149 offset:1024
	ds_read_b128 v[154:157], v149 offset:2048
	ds_read_b128 v[158:161], v149 offset:3072
	v_add_u32_e32 v149, s96, v147
	ds_read_b128 v[162:165], v149
	ds_read_b128 v[166:169], v149 offset:1024
	ds_read_b128 v[170:173], v149 offset:2048
	ds_read_b128 v[174:177], v149 offset:3072
	s_add_u32 s40, s40, 0x80000
	s_addc_u32 s41, s41, 0
	s_mov_b32 m0, s37
	v_lshl_add_u64 v[218:219], s[40:41], 0, v[130:131]
	ds_read_b128 v[178:181], v148 offset:32768
	ds_read_b128 v[182:185], v148 offset:33792
	ds_read_b128 v[186:189], v148 offset:34816
	ds_read_b128 v[190:193], v148 offset:35840
	ds_read_b128 v[194:197], v148 offset:36864
	ds_read_b128 v[198:201], v148 offset:37888
	ds_read_b128 v[202:205], v148 offset:38912
	ds_read_b128 v[206:209], v148 offset:39936
	global_load_lds_dwordx4 v[218:219], off
	v_lshl_add_u64 v[218:219], s[40:41], 0, v[134:135]
	s_mov_b32 m0, s42
	s_nop 0
	global_load_lds_dwordx4 v[218:219], off
	s_waitcnt vmcnt(8)
	s_waitcnt lgkmcnt(0)
	s_barrier
	s_setprio 1
	s_waitcnt lgkmcnt(0)
	v_mfma_f32_16x16x32_bf16 v[126:129], v[142:145], v[178:181], v[126:129]
	v_mfma_f32_16x16x32_bf16 v[122:125], v[154:157], v[178:181], v[122:125]
	v_mfma_f32_16x16x32_bf16 v[110:113], v[142:145], v[186:189], v[110:113]
	v_mfma_f32_16x16x32_bf16 v[106:109], v[154:157], v[186:189], v[106:109]
	v_mfma_f32_16x16x32_bf16 v[94:97], v[142:145], v[194:197], v[94:97]
	v_mfma_f32_16x16x32_bf16 v[90:93], v[154:157], v[194:197], v[90:93]
	v_mfma_f32_16x16x32_bf16 v[78:81], v[142:145], v[202:205], v[78:81]
	v_mfma_f32_16x16x32_bf16 v[74:77], v[154:157], v[202:205], v[74:77]
	v_mfma_f32_16x16x32_bf16 v[126:129], v[150:153], v[182:185], v[126:129]
	v_mfma_f32_16x16x32_bf16 v[122:125], v[158:161], v[182:185], v[122:125]
	v_mfma_f32_16x16x32_bf16 v[110:113], v[150:153], v[190:193], v[110:113]
	v_mfma_f32_16x16x32_bf16 v[106:109], v[158:161], v[190:193], v[106:109]
	v_mfma_f32_16x16x32_bf16 v[94:97], v[150:153], v[198:201], v[94:97]
	v_mfma_f32_16x16x32_bf16 v[90:93], v[158:161], v[198:201], v[90:93]
	v_mfma_f32_16x16x32_bf16 v[78:81], v[150:153], v[206:209], v[78:81]
	v_mfma_f32_16x16x32_bf16 v[74:77], v[158:161], v[206:209], v[74:77]
	s_setprio 0
	s_setprio 1
	v_mfma_f32_16x16x32_bf16 v[118:121], v[162:165], v[178:181], v[118:121]
	v_mfma_f32_16x16x32_bf16 v[114:117], v[170:173], v[178:181], v[114:117]
	v_mfma_f32_16x16x32_bf16 v[102:105], v[162:165], v[186:189], v[102:105]
	v_mfma_f32_16x16x32_bf16 v[98:101], v[170:173], v[186:189], v[98:101]
	v_mfma_f32_16x16x32_bf16 v[86:89], v[162:165], v[194:197], v[86:89]
	v_mfma_f32_16x16x32_bf16 v[82:85], v[170:173], v[194:197], v[82:85]
	v_mfma_f32_16x16x32_bf16 v[70:73], v[162:165], v[202:205], v[70:73]
	v_mfma_f32_16x16x32_bf16 v[66:69], v[170:173], v[202:205], v[66:69]
	v_mfma_f32_16x16x32_bf16 v[118:121], v[166:169], v[182:185], v[118:121]
	v_mfma_f32_16x16x32_bf16 v[114:117], v[174:177], v[182:185], v[114:117]
	v_mfma_f32_16x16x32_bf16 v[102:105], v[166:169], v[190:193], v[102:105]
	v_mfma_f32_16x16x32_bf16 v[98:101], v[174:177], v[190:193], v[98:101]
	v_mfma_f32_16x16x32_bf16 v[86:89], v[166:169], v[198:201], v[86:89]
	v_mfma_f32_16x16x32_bf16 v[82:85], v[174:177], v[198:201], v[82:85]
	v_mfma_f32_16x16x32_bf16 v[70:73], v[166:169], v[206:209], v[70:73]
	v_mfma_f32_16x16x32_bf16 v[66:69], v[174:177], v[206:209], v[66:69]
	s_setprio 0
	s_barrier
; #define PG8_STAGE(bufoff, gbase, voff) do { _Pragma("unroll") for (int _i = 0; _i < 2; ++_i) \
;         __builtin_amdgcn_global_load_lds((const unsigned*)((const char*)(gbase) + (voff)[_i]), (PG8_LAS unsigned*)(lds + (bufoff) + ldsw + _i * 8192), 16, 0, 0); } while (0)
; #define PG8_LDA(dst, b, h) do { _Pragma("unroll") for (int m = 0; m < 4; ++m) _Pragma("unroll") for (int k = 0; k < 2; ++k) dst[m][k] = *(const PG8_LAS bf16x8*)(lds + PG8_SA(b, h) + aoff + m * 2048 + k * 1024); } while (0)
; #define PG8_MMA(ai, bj, At, Bt) do { __builtin_amdgcn_s_setprio(1); _Pragma("unroll") for (int m = 0; m < 4; ++m) _Pragma("unroll") for (int n = 0; n < 2; ++n) _Pragma("unroll") for (int k = 0; k < 2; ++k) \
;         acc[ai][bj][m][n] = __builtin_amdgcn_mfma_f32_16x16x32_bf16(Bt[n][k], At[m][k], acc[ai][bj][m][n], 0, 0, 0); __builtin_amdgcn_s_setprio(0); } while (0)
; #define PG8_WAIT_V(n) asm volatile("s_waitcnt vmcnt(" #n ")" ::: "memory")
; #define PG8_WAIT_L(n) asm volatile("s_waitcnt lgkmcnt(" #n ")" ::: "memory")
; #define PG8_BAR __builtin_amdgcn_s_barrier()
; #define PG8_SCHED __builtin_amdgcn_sched_barrier(0)
; template <class Epi, class Sched, bool ALIGN_EPI = false, bool SP2 = false>
; __device__ __forceinline__ void gemm_phase(PG8_LAS unsigned char* lds, const Gemm g, const Sched& S, const Epi& E, int wave_s) {
;     ...
;         for (int t = 0; t < nt; t += 2) {
;     ...
;             PG8_LDA(At, 1, 1); PG8_STAGE(PG8_SB(1, 0), b3, voffB); PG8_STAGE(PG8_SB(1, 1), b3 + hstepB, voffB); PG8_STAGE(PG8_SA(1, 0), a3, voffA);
;             PG8_WAIT_V(8); PG8_WAIT_L(0); PG8_BAR; PG8_MMA(1, 0, At, B0); PG8_MMA(1, 1, At, B1); PG8_BAR; PG8_SCHED;
	s_add_i32 s40, s95, s34
	v_lshl_add_u64 v[210:211], v[210:211], 0, s[60:61]
	s_mov_b32 m0, s40
	ds_read_b128 v[178:181], v148 offset:49152
	ds_read_b128 v[182:185], v148 offset:50176
	ds_read_b128 v[186:189], v148 offset:51200
	ds_read_b128 v[190:193], v148 offset:52224
	ds_read_b128 v[194:197], v148 offset:53248
	ds_read_b128 v[198:201], v148 offset:54272
	ds_read_b128 v[202:205], v148 offset:55296
	ds_read_b128 v[206:209], v148 offset:56320
	global_load_lds_dwordx4 v[210:211], off
	s_add_i32 m0, s40, 0x2000
	s_add_u32 s30, s30, 0x80080
	v_lshl_add_u64 v[210:211], v[212:213], 0, s[60:61]
	s_addc_u32 s31, s31, 0
	s_add_i32 s40, s96, s34
	global_load_lds_dwordx4 v[210:211], off
	v_lshl_add_u64 v[210:211], s[30:31], 0, v[132:133]
	s_mov_b32 m0, s40
	s_nop 0
	global_load_lds_dwordx4 v[210:211], off
	v_lshl_add_u64 v[210:211], s[30:31], 0, v[136:137]
	s_add_i32 m0, s40, 0x2000
	s_nop 0
	global_load_lds_dwordx4 v[210:211], off
	v_lshl_add_u64 v[210:211], v[214:215], 0, s[60:61]
	s_mov_b32 m0, s45
	s_nop 0
	global_load_lds_dwordx4 v[210:211], off
	v_lshl_add_u64 v[210:211], v[216:217], 0, s[60:61]
	s_mov_b32 m0, s46
	s_nop 0
	global_load_lds_dwordx4 v[210:211], off
	s_waitcnt vmcnt(8)
	s_waitcnt lgkmcnt(0)
	s_barrier
	s_setprio 1
	s_waitcnt lgkmcnt(0)
	v_mfma_f32_16x16x32_bf16 v[62:65], v[142:145], v[178:181], v[62:65]
	v_mfma_f32_16x16x32_bf16 v[58:61], v[154:157], v[178:181], v[58:61]
	v_mfma_f32_16x16x32_bf16 v[46:49], v[142:145], v[186:189], v[46:49]
	v_mfma_f32_16x16x32_bf16 v[42:45], v[154:157], v[186:189], v[42:45]
	v_mfma_f32_16x16x32_bf16 v[30:33], v[142:145], v[194:197], v[30:33]
	v_mfma_f32_16x16x32_bf16 v[26:29], v[154:157], v[194:197], v[26:29]
	v_mfma_f32_16x16x32_bf16 v[14:17], v[142:145], v[202:205], v[14:17]
	v_mfma_f32_16x16x32_bf16 v[10:13], v[154:157], v[202:205], v[10:13]
	v_mfma_f32_16x16x32_bf16 v[62:65], v[150:153], v[182:185], v[62:65]
	v_mfma_f32_16x16x32_bf16 v[58:61], v[158:161], v[182:185], v[58:61]
	v_mfma_f32_16x16x32_bf16 v[46:49], v[150:153], v[190:193], v[46:49]
	v_mfma_f32_16x16x32_bf16 v[42:45], v[158:161], v[190:193], v[42:45]
	v_mfma_f32_16x16x32_bf16 v[30:33], v[150:153], v[198:201], v[30:33]
	v_mfma_f32_16x16x32_bf16 v[26:29], v[158:161], v[198:201], v[26:29]
	v_mfma_f32_16x16x32_bf16 v[14:17], v[150:153], v[206:209], v[14:17]
	v_mfma_f32_16x16x32_bf16 v[10:13], v[158:161], v[206:209], v[10:13]
	s_setprio 0
	s_setprio 1
	v_mfma_f32_16x16x32_bf16 v[54:57], v[162:165], v[178:181], v[54:57]
	v_mfma_f32_16x16x32_bf16 v[50:53], v[170:173], v[178:181], v[50:53]
	v_mfma_f32_16x16x32_bf16 v[38:41], v[162:165], v[186:189], v[38:41]
	v_mfma_f32_16x16x32_bf16 v[34:37], v[170:173], v[186:189], v[34:37]
	v_mfma_f32_16x16x32_bf16 v[22:25], v[162:165], v[194:197], v[22:25]
	v_mfma_f32_16x16x32_bf16 v[18:21], v[170:173], v[194:197], v[18:21]
	v_mfma_f32_16x16x32_bf16 v[6:9], v[162:165], v[202:205], v[6:9]
	v_mfma_f32_16x16x32_bf16 v[2:5], v[170:173], v[202:205], v[2:5]
	v_mfma_f32_16x16x32_bf16 v[54:57], v[166:169], v[182:185], v[54:57]
	v_mfma_f32_16x16x32_bf16 v[50:53], v[174:177], v[182:185], v[50:53]
	v_mfma_f32_16x16x32_bf16 v[38:41], v[166:169], v[190:193], v[38:41]
	v_mfma_f32_16x16x32_bf16 v[34:37], v[174:177], v[190:193], v[34:37]
	v_mfma_f32_16x16x32_bf16 v[22:25], v[166:169], v[198:201], v[22:25]
	v_mfma_f32_16x16x32_bf16 v[18:21], v[174:177], v[198:201], v[18:21]
	v_mfma_f32_16x16x32_bf16 v[6:9], v[166:169], v[206:209], v[6:9]
	v_mfma_f32_16x16x32_bf16 v[2:5], v[174:177], v[206:209], v[2:5]
	s_setprio 0
	s_barrier
	s_add_i32 s94, s94, 2
	s_add_u32 s4, s4, 0x100
	s_addc_u32 s5, s5, 0
	s_add_u32 s15, s15, 0x100
	s_addc_u32 s21, s21, 0
	s_cmp_gt_u32 s94, 29

; #define PG8_STAGE(bufoff, gbase, voff) do { _Pragma("unroll") for (int _i = 0; _i < 2; ++_i) \
;         __builtin_amdgcn_global_load_lds((const unsigned*)((const char*)(gbase) + (voff)[_i]), (PG8_LAS unsigned*)(lds + (bufoff) + ldsw + _i * 8192), 16, 0, 0); } while (0)
; #define PG8_LDA(dst, b, h) do { _Pragma("unroll") for (int m = 0; m < 4; ++m) _Pragma("unroll") for (int k = 0; k < 2; ++k) dst[m][k] = *(const PG8_LAS bf16x8*)(lds + PG8_SA(b, h) + aoff + m * 2048 + k * 1024); } while (0)
; #define PG8_LDB(dst, b, h) do { _Pragma("unroll") for (int n = 0; n < 2; ++n) _Pragma("unroll") for (int k = 0; k < 2; ++k) dst[n][k] = *(const PG8_LAS bf16x8*)(lds + PG8_SB(b, h) + boff + n * 2048 + k * 1024); } while (0)
; #define PG8_MMA(ai, bj, At, Bt) do { __builtin_amdgcn_s_setprio(1); _Pragma("unroll") for (int m = 0; m < 4; ++m) _Pragma("unroll") for (int n = 0; n < 2; ++n) _Pragma("unroll") for (int k = 0; k < 2; ++k) \
;         acc[ai][bj][m][n] = __builtin_amdgcn_mfma_f32_16x16x32_bf16(Bt[n][k], At[m][k], acc[ai][bj][m][n], 0, 0, 0); __builtin_amdgcn_s_setprio(0); } while (0)
; #define PG8_WAIT_V(n) asm volatile("s_waitcnt vmcnt(" #n ")" ::: "memory")
; #define PG8_WAIT_L(n) asm volatile("s_waitcnt lgkmcnt(" #n ")" ::: "memory")
; #define PG8_BAR __builtin_amdgcn_s_barrier()
; #define PG8_SCHED __builtin_amdgcn_sched_barrier(0)
; template <class Epi, class Sched, bool ALIGN_EPI = false, bool SP2 = false>
; __device__ __forceinline__ void gemm_phase(PG8_LAS unsigned char* lds, const Gemm g, const Sched& S, const Epi& E, int wave_s) {
;     ...
;             PG8_LDB(B0, 0, 0); PG8_LDB(B1, 0, 1); PG8_SCHED; PG8_LDA(At, 0, 0); PG8_STAGE(PG8_SA(1, 1), a1 + hstepA, voffA);
;             PG8_WAIT_V(8); PG8_WAIT_L(0); PG8_BAR; PG8_MMA(0, 0, At, B0); PG8_MMA(0, 1, At, B1); PG8_BAR; PG8_SCHED;
;             PG8_LDA(At, 0, 1); PG8_STAGE(PG8_SB(0, 0), b2, voffB); PG8_STAGE(PG8_SB(0, 1), b2 + hstepB, voffB); PG8_STAGE(PG8_SA(0, 0), a2, voffA);
;             PG8_WAIT_V(8); PG8_WAIT_L(0); PG8_BAR; PG8_MMA(1, 0, At, B0); PG8_MMA(1, 1, At, B1); PG8_BAR; PG8_SCHED;
.LBB0_601:
	s_ashr_i32 s21, s20, 31
	s_lshl_b64 s[2:3], s[20:21], 20
	s_add_u32 s88, s22, s2
	s_addc_u32 s89, s23, s3
	s_and_b64 s[2:3], s[4:5], exec
	s_cselect_b32 s2, s89, s31
	s_cselect_b32 s3, s88, s30
	s_add_u32 s4, s40, 0x80080
	s_addc_u32 s5, s41, 0
	s_add_u32 s21, s30, 0x100
	s_addc_u32 s27, s31, 0
	s_mov_b32 s81, -2
	s_add_u32 s30, s4, 0xfff80080
	s_addc_u32 s31, s5, -1
	s_add_i32 s84, 0, 0x10000
	s_cmp_eq_u32 s81, 28
	s_cselect_b32 s41, s29, s31
	s_cselect_b32 s40, s28, s30
	s_cselect_b32 s31, s2, s27
	s_cselect_b32 s30, s3, s21
	s_add_i32 s90, 0, 0x14000
	v_add_u32_e32 v134, s84, v207
	v_add_u32_e32 v158, s90, v207
	ds_read_b128 v[118:121], v134
	ds_read_b128 v[126:129], v134 offset:1024
	ds_read_b128 v[130:133], v134 offset:2048
	ds_read_b128 v[134:137], v134 offset:3072
	ds_read_b128 v[138:141], v158
	ds_read_b128 v[142:145], v158 offset:1024
	ds_read_b128 v[154:157], v158 offset:2048
	ds_read_b128 v[158:161], v158 offset:3072
	v_lshl_add_u64 v[210:211], s[4:5], 0, v[198:199]
	s_add_i32 m0, s35, 0xc000
	ds_read_b128 v[162:165], v208
	ds_read_b128 v[166:169], v208 offset:1024
	ds_read_b128 v[170:173], v208 offset:2048
	ds_read_b128 v[174:177], v208 offset:3072
	ds_read_b128 v[178:181], v208 offset:4096
	ds_read_b128 v[182:185], v208 offset:5120
	ds_read_b128 v[186:189], v208 offset:6144
	ds_read_b128 v[202:205], v208 offset:7168
	global_load_lds_dwordx4 v[210:211], off
	v_lshl_add_u64 v[210:211], s[4:5], 0, v[200:201]
	s_add_i32 m0, s35, 0xe000
	s_nop 0
	global_load_lds_dwordx4 v[210:211], off
	s_waitcnt vmcnt(8)
	s_waitcnt lgkmcnt(0)
	s_barrier
	s_setprio 1
	s_waitcnt lgkmcnt(0)
	v_mfma_f32_16x16x32_bf16 v[150:153], v[118:121], v[162:165], 0
	v_mfma_f32_16x16x32_bf16 v[146:149], v[130:133], v[162:165], 0
	v_mfma_f32_16x16x32_bf16 v[110:113], v[118:121], v[170:173], 0
	v_mfma_f32_16x16x32_bf16 v[106:109], v[130:133], v[170:173], 0
	v_mfma_f32_16x16x32_bf16 v[94:97], v[118:121], v[178:181], 0
	v_mfma_f32_16x16x32_bf16 v[90:93], v[130:133], v[178:181], 0
	v_mfma_f32_16x16x32_bf16 v[78:81], v[118:121], v[186:189], 0
	v_mfma_f32_16x16x32_bf16 v[74:77], v[130:133], v[186:189], 0
	v_mfma_f32_16x16x32_bf16 v[150:153], v[126:129], v[166:169], v[150:153]
	v_mfma_f32_16x16x32_bf16 v[146:149], v[134:137], v[166:169], v[146:149]
	v_mfma_f32_16x16x32_bf16 v[110:113], v[126:129], v[174:177], v[110:113]
	v_mfma_f32_16x16x32_bf16 v[106:109], v[134:137], v[174:177], v[106:109]
	v_mfma_f32_16x16x32_bf16 v[94:97], v[126:129], v[182:185], v[94:97]
	v_mfma_f32_16x16x32_bf16 v[90:93], v[134:137], v[182:185], v[90:93]
	v_mfma_f32_16x16x32_bf16 v[78:81], v[126:129], v[202:205], v[78:81]
	v_mfma_f32_16x16x32_bf16 v[74:77], v[134:137], v[202:205], v[74:77]
	s_setprio 0
	s_setprio 1
	v_mfma_f32_16x16x32_bf16 v[122:125], v[138:141], v[162:165], 0
	v_mfma_f32_16x16x32_bf16 v[114:117], v[154:157], v[162:165], 0
	v_mfma_f32_16x16x32_bf16 v[102:105], v[138:141], v[170:173], 0
	v_mfma_f32_16x16x32_bf16 v[98:101], v[154:157], v[170:173], 0
	v_mfma_f32_16x16x32_bf16 v[86:89], v[138:141], v[178:181], 0
	v_mfma_f32_16x16x32_bf16 v[82:85], v[154:157], v[178:181], 0
	v_mfma_f32_16x16x32_bf16 v[70:73], v[138:141], v[186:189], 0
	v_mfma_f32_16x16x32_bf16 v[66:69], v[154:157], v[186:189], 0
	v_mfma_f32_16x16x32_bf16 v[122:125], v[142:145], v[166:169], v[122:125]
	v_mfma_f32_16x16x32_bf16 v[114:117], v[158:161], v[166:169], v[114:117]
	v_mfma_f32_16x16x32_bf16 v[102:105], v[142:145], v[174:177], v[102:105]
	v_mfma_f32_16x16x32_bf16 v[98:101], v[158:161], v[174:177], v[98:101]
	v_mfma_f32_16x16x32_bf16 v[86:89], v[142:145], v[182:185], v[86:89]
	v_mfma_f32_16x16x32_bf16 v[82:85], v[158:161], v[182:185], v[82:85]
	v_mfma_f32_16x16x32_bf16 v[70:73], v[142:145], v[202:205], v[70:73]
	v_mfma_f32_16x16x32_bf16 v[66:69], v[158:161], v[202:205], v[66:69]
	s_setprio 0
	s_barrier
	s_add_i32 s84, s84, s34
	v_lshl_add_u64 v[210:211], s[30:31], 0, v[194:195]
	s_mov_b32 m0, s84
	ds_read_b128 v[162:165], v208 offset:16384
	ds_read_b128 v[166:169], v208 offset:17408
	ds_read_b128 v[170:173], v208 offset:18432
	ds_read_b128 v[174:177], v208 offset:19456
	ds_read_b128 v[178:181], v208 offset:20480
	ds_read_b128 v[182:185], v208 offset:21504
	ds_read_b128 v[186:189], v208 offset:22528
	ds_read_b128 v[202:205], v208 offset:23552
	global_load_lds_dwordx4 v[210:211], off
	s_add_i32 m0, s84, 0x2000
	s_add_u32 s84, s30, 0x80000
	v_lshl_add_u64 v[212:213], s[30:31], 0, v[190:191]
	s_addc_u32 s85, s31, 0
	s_add_i32 s90, s90, s34
	global_load_lds_dwordx4 v[212:213], off
	v_lshl_add_u64 v[214:215], s[84:85], 0, v[194:195]
	s_mov_b32 m0, s90
	v_lshl_add_u64 v[216:217], s[40:41], 0, v[192:193]
	global_load_lds_dwordx4 v[214:215], off
	v_lshl_add_u64 v[214:215], s[84:85], 0, v[190:191]
	s_add_i32 m0, s90, 0x2000
	s_nop 0
	global_load_lds_dwordx4 v[214:215], off
	v_lshl_add_u64 v[214:215], s[40:41], 0, v[196:197]
	s_mov_b32 m0, s35
	s_nop 0
	global_load_lds_dwordx4 v[214:215], off
	s_mov_b32 m0, s36
	s_nop 0
	global_load_lds_dwordx4 v[216:217], off
	s_waitcnt vmcnt(8)
	s_waitcnt lgkmcnt(0)
	s_barrier
; #define PG8_STAGE(bufoff, gbase, voff) do { _Pragma("unroll") for (int _i = 0; _i < 2; ++_i) \
;         __builtin_amdgcn_global_load_lds((const unsigned*)((const char*)(gbase) + (voff)[_i]), (PG8_LAS unsigned*)(lds + (bufoff) + ldsw + _i * 8192), 16, 0, 0); } while (0)
; #define PG8_LDA(dst, b, h) do { _Pragma("unroll") for (int m = 0; m < 4; ++m) _Pragma("unroll") for (int k = 0; k < 2; ++k) dst[m][k] = *(const PG8_LAS bf16x8*)(lds + PG8_SA(b, h) + aoff + m * 2048 + k * 1024); } while (0)
; #define PG8_LDB(dst, b, h) do { _Pragma("unroll") for (int n = 0; n < 2; ++n) _Pragma("unroll") for (int k = 0; k < 2; ++k) dst[n][k] = *(const PG8_LAS bf16x8*)(lds + PG8_SB(b, h) + boff + n * 2048 + k * 1024); } while (0)
; #define PG8_MMA(ai, bj, At, Bt) do { __builtin_amdgcn_s_setprio(1); _Pragma("unroll") for (int m = 0; m < 4; ++m) _Pragma("unroll") for (int n = 0; n < 2; ++n) _Pragma("unroll") for (int k = 0; k < 2; ++k) \
;         acc[ai][bj][m][n] = __builtin_amdgcn_mfma_f32_16x16x32_bf16(Bt[n][k], At[m][k], acc[ai][bj][m][n], 0, 0, 0); __builtin_amdgcn_s_setprio(0); } while (0)
; #define PG8_WAIT_V(n) asm volatile("s_waitcnt vmcnt(" #n ")" ::: "memory")
; #define PG8_WAIT_L(n) asm volatile("s_waitcnt lgkmcnt(" #n ")" ::: "memory")
; #define PG8_BAR __builtin_amdgcn_s_barrier()
; #define PG8_SCHED __builtin_amdgcn_sched_barrier(0)
; template <class Epi, class Sched, bool ALIGN_EPI = false, bool SP2 = false>
; __device__ __forceinline__ void gemm_phase(PG8_LAS unsigned char* lds, const Gemm g, const Sched& S, const Epi& E, int wave_s) {
;     ...
;             PG8_WAIT_V(8); PG8_WAIT_L(0); PG8_BAR; PG8_MMA(1, 0, At, B0); PG8_MMA(1, 1, At, B1); PG8_BAR; PG8_SCHED;
;             PG8_LDB(B0, 1, 0); PG8_LDB(B1, 1, 1); PG8_SCHED; PG8_LDA(At, 1, 0); PG8_STAGE(PG8_SA(0, 1), a2 + hstepA, voffA);
;             PG8_WAIT_V(8); PG8_WAIT_L(0); PG8_BAR; PG8_MMA(0, 0, At, B0); PG8_MMA(0, 1, At, B1); PG8_BAR; PG8_SCHED;
	s_setprio 1
	s_waitcnt lgkmcnt(0)
	v_mfma_f32_16x16x32_bf16 v[62:65], v[118:121], v[162:165], 0
	v_mfma_f32_16x16x32_bf16 v[58:61], v[130:133], v[162:165], 0
	v_mfma_f32_16x16x32_bf16 v[46:49], v[118:121], v[170:173], 0
	v_mfma_f32_16x16x32_bf16 v[42:45], v[130:133], v[170:173], 0
	v_mfma_f32_16x16x32_bf16 v[30:33], v[118:121], v[178:181], 0
	v_mfma_f32_16x16x32_bf16 v[26:29], v[130:133], v[178:181], 0
	v_mfma_f32_16x16x32_bf16 v[14:17], v[118:121], v[186:189], 0
	v_mfma_f32_16x16x32_bf16 v[10:13], v[130:133], v[186:189], 0
	v_mfma_f32_16x16x32_bf16 v[62:65], v[126:129], v[166:169], v[62:65]
	v_mfma_f32_16x16x32_bf16 v[58:61], v[134:137], v[166:169], v[58:61]
	v_mfma_f32_16x16x32_bf16 v[46:49], v[126:129], v[174:177], v[46:49]
	v_mfma_f32_16x16x32_bf16 v[42:45], v[134:137], v[174:177], v[42:45]
	v_mfma_f32_16x16x32_bf16 v[30:33], v[126:129], v[182:185], v[30:33]
	v_mfma_f32_16x16x32_bf16 v[26:29], v[134:137], v[182:185], v[26:29]
	v_mfma_f32_16x16x32_bf16 v[14:17], v[126:129], v[202:205], v[14:17]
	v_mfma_f32_16x16x32_bf16 v[10:13], v[134:137], v[202:205], v[10:13]
	s_setprio 0
	s_setprio 1
	v_mfma_f32_16x16x32_bf16 v[54:57], v[138:141], v[162:165], 0
	v_mfma_f32_16x16x32_bf16 v[50:53], v[154:157], v[162:165], 0
	v_mfma_f32_16x16x32_bf16 v[38:41], v[138:141], v[170:173], 0
	v_mfma_f32_16x16x32_bf16 v[34:37], v[154:157], v[170:173], 0
	v_mfma_f32_16x16x32_bf16 v[22:25], v[138:141], v[178:181], 0
	v_mfma_f32_16x16x32_bf16 v[18:21], v[154:157], v[178:181], 0
	v_mfma_f32_16x16x32_bf16 v[6:9], v[138:141], v[186:189], 0
	v_mfma_f32_16x16x32_bf16 v[2:5], v[154:157], v[186:189], 0
	v_mfma_f32_16x16x32_bf16 v[54:57], v[142:145], v[166:169], v[54:57]
	v_mfma_f32_16x16x32_bf16 v[50:53], v[158:161], v[166:169], v[50:53]
	v_mfma_f32_16x16x32_bf16 v[38:41], v[142:145], v[174:177], v[38:41]
	v_mfma_f32_16x16x32_bf16 v[34:37], v[158:161], v[174:177], v[34:37]
	v_mfma_f32_16x16x32_bf16 v[22:25], v[142:145], v[182:185], v[22:25]
	v_mfma_f32_16x16x32_bf16 v[18:21], v[158:161], v[182:185], v[18:21]
	v_mfma_f32_16x16x32_bf16 v[6:9], v[142:145], v[202:205], v[6:9]
	v_mfma_f32_16x16x32_bf16 v[2:5], v[158:161], v[202:205], v[2:5]
	s_setprio 0
	s_barrier
	s_add_i32 s84, 0, 0x18000
	s_add_i32 s85, 0, 0x1c000
	v_add_u32_e32 v134, s84, v207
	v_add_u32_e32 v158, s85, v207
	ds_read_b128 v[118:121], v134
	ds_read_b128 v[126:129], v134 offset:1024
	ds_read_b128 v[130:133], v134 offset:2048
	ds_read_b128 v[134:137], v134 offset:3072
	ds_read_b128 v[138:141], v158
	ds_read_b128 v[142:145], v158 offset:1024
	ds_read_b128 v[154:157], v158 offset:2048
	ds_read_b128 v[158:161], v158 offset:3072
	s_add_u32 s40, s40, 0x80000
	s_addc_u32 s41, s41, 0
	s_mov_b32 m0, s37
	v_lshl_add_u64 v[218:219], s[40:41], 0, v[196:197]
	ds_read_b128 v[162:165], v208 offset:32768
	ds_read_b128 v[166:169], v208 offset:33792
	ds_read_b128 v[170:173], v208 offset:34816
	ds_read_b128 v[174:177], v208 offset:35840
	ds_read_b128 v[178:181], v208 offset:36864
	ds_read_b128 v[182:185], v208 offset:37888
	ds_read_b128 v[186:189], v208 offset:38912
	ds_read_b128 v[202:205], v208 offset:39936
	global_load_lds_dwordx4 v[218:219], off
	v_lshl_add_u64 v[218:219], s[40:41], 0, v[192:193]
	s_mov_b32 m0, s42
	s_nop 0
	global_load_lds_dwordx4 v[218:219], off
	s_waitcnt vmcnt(8)
	s_waitcnt lgkmcnt(0)
	s_barrier
	s_setprio 1
	s_waitcnt lgkmcnt(0)
	v_mfma_f32_16x16x32_bf16 v[150:153], v[118:121], v[162:165], v[150:153]
	v_mfma_f32_16x16x32_bf16 v[146:149], v[130:133], v[162:165], v[146:149]
	v_mfma_f32_16x16x32_bf16 v[110:113], v[118:121], v[170:173], v[110:113]
	v_mfma_f32_16x16x32_bf16 v[106:109], v[130:133], v[170:173], v[106:109]
	v_mfma_f32_16x16x32_bf16 v[94:97], v[118:121], v[178:181], v[94:97]
	v_mfma_f32_16x16x32_bf16 v[90:93], v[130:133], v[178:181], v[90:93]
	v_mfma_f32_16x16x32_bf16 v[78:81], v[118:121], v[186:189], v[78:81]
	v_mfma_f32_16x16x32_bf16 v[74:77], v[130:133], v[186:189], v[74:77]
	v_mfma_f32_16x16x32_bf16 v[150:153], v[126:129], v[166:169], v[150:153]
	v_mfma_f32_16x16x32_bf16 v[146:149], v[134:137], v[166:169], v[146:149]
	v_mfma_f32_16x16x32_bf16 v[110:113], v[126:129], v[174:177], v[110:113]
	v_mfma_f32_16x16x32_bf16 v[106:109], v[134:137], v[174:177], v[106:109]
	v_mfma_f32_16x16x32_bf16 v[94:97], v[126:129], v[182:185], v[94:97]
	v_mfma_f32_16x16x32_bf16 v[90:93], v[134:137], v[182:185], v[90:93]
	v_mfma_f32_16x16x32_bf16 v[78:81], v[126:129], v[202:205], v[78:81]
	v_mfma_f32_16x16x32_bf16 v[74:77], v[134:137], v[202:205], v[74:77]
	s_setprio 0
	s_setprio 1
	v_mfma_f32_16x16x32_bf16 v[122:125], v[138:141], v[162:165], v[122:125]
	v_mfma_f32_16x16x32_bf16 v[114:117], v[154:157], v[162:165], v[114:117]
	v_mfma_f32_16x16x32_bf16 v[102:105], v[138:141], v[170:173], v[102:105]
	v_mfma_f32_16x16x32_bf16 v[98:101], v[154:157], v[170:173], v[98:101]
	v_mfma_f32_16x16x32_bf16 v[86:89], v[138:141], v[178:181], v[86:89]
	v_mfma_f32_16x16x32_bf16 v[82:85], v[154:157], v[178:181], v[82:85]
	v_mfma_f32_16x16x32_bf16 v[70:73], v[138:141], v[186:189], v[70:73]
	v_mfma_f32_16x16x32_bf16 v[66:69], v[154:157], v[186:189], v[66:69]
	v_mfma_f32_16x16x32_bf16 v[122:125], v[142:145], v[166:169], v[122:125]
	v_mfma_f32_16x16x32_bf16 v[114:117], v[158:161], v[166:169], v[114:117]
	v_mfma_f32_16x16x32_bf16 v[102:105], v[142:145], v[174:177], v[102:105]
	v_mfma_f32_16x16x32_bf16 v[98:101], v[158:161], v[174:177], v[98:101]
	v_mfma_f32_16x16x32_bf16 v[86:89], v[142:145], v[182:185], v[86:89]
	v_mfma_f32_16x16x32_bf16 v[82:85], v[158:161], v[182:185], v[82:85]
	v_mfma_f32_16x16x32_bf16 v[70:73], v[142:145], v[202:205], v[70:73]
	v_mfma_f32_16x16x32_bf16 v[66:69], v[158:161], v[202:205], v[66:69]
	s_setprio 0
	s_barrier
; #define PG8_STAGE(bufoff, gbase, voff) do { _Pragma("unroll") for (int _i = 0; _i < 2; ++_i) \
;         __builtin_amdgcn_global_load_lds((const unsigned*)((const char*)(gbase) + (voff)[_i]), (PG8_LAS unsigned*)(lds + (bufoff) + ldsw + _i * 8192), 16, 0, 0); } while (0)
; #define PG8_LDA(dst, b, h) do { _Pragma("unroll") for (int m = 0; m < 4; ++m) _Pragma("unroll") for (int k = 0; k < 2; ++k) dst[m][k] = *(const PG8_LAS bf16x8*)(lds + PG8_SA(b, h) + aoff + m * 2048 + k * 1024); } while (0)
; #define PG8_MMA(ai, bj, At, Bt) do { __builtin_amdgcn_s_setprio(1); _Pragma("unroll") for (int m = 0; m < 4; ++m) _Pragma("unroll") for (int n = 0; n < 2; ++n) _Pragma("unroll") for (int k = 0; k < 2; ++k) \
;         acc[ai][bj][m][n] = __builtin_amdgcn_mfma_f32_16x16x32_bf16(Bt[n][k], At[m][k], acc[ai][bj][m][n], 0, 0, 0); __builtin_amdgcn_s_setprio(0); } while (0)
; #define PG8_WAIT_V(n) asm volatile("s_waitcnt vmcnt(" #n ")" ::: "memory")
; #define PG8_WAIT_L(n) asm volatile("s_waitcnt lgkmcnt(" #n ")" ::: "memory")
; #define PG8_BAR __builtin_amdgcn_s_barrier()
; #define PG8_SCHED __builtin_amdgcn_sched_barrier(0)
; template <class Epi, class Sched, bool ALIGN_EPI = false, bool SP2 = false>
; __device__ __forceinline__ void gemm_phase(PG8_LAS unsigned char* lds, const Gemm g, const Sched& S, const Epi& E, int wave_s) {
;     ...
;         for (int t = 0; t < nt; t += 2) {
;     ...
;             PG8_LDA(At, 1, 1); PG8_STAGE(PG8_SB(1, 0), b3, voffB); PG8_STAGE(PG8_SB(1, 1), b3 + hstepB, voffB); PG8_STAGE(PG8_SA(1, 0), a3, voffA);
;             PG8_WAIT_V(8); PG8_WAIT_L(0); PG8_BAR; PG8_MMA(1, 0, At, B0); PG8_MMA(1, 1, At, B1); PG8_BAR; PG8_SCHED;
	s_add_i32 s40, s84, s34
	v_lshl_add_u64 v[210:211], v[210:211], 0, s[60:61]
	s_mov_b32 m0, s40
	ds_read_b128 v[162:165], v208 offset:49152
	ds_read_b128 v[166:169], v208 offset:50176
	ds_read_b128 v[170:173], v208 offset:51200
	ds_read_b128 v[174:177], v208 offset:52224
	ds_read_b128 v[178:181], v208 offset:53248
	ds_read_b128 v[182:185], v208 offset:54272
	ds_read_b128 v[186:189], v208 offset:55296
	ds_read_b128 v[202:205], v208 offset:56320
	global_load_lds_dwordx4 v[210:211], off
	s_add_i32 m0, s40, 0x2000
	s_add_u32 s30, s30, 0x80080
	v_lshl_add_u64 v[210:211], v[212:213], 0, s[60:61]
	s_addc_u32 s31, s31, 0
	s_add_i32 s40, s85, s34
	global_load_lds_dwordx4 v[210:211], off
	v_lshl_add_u64 v[210:211], s[30:31], 0, v[194:195]
	s_mov_b32 m0, s40
	s_nop 0
	global_load_lds_dwordx4 v[210:211], off
	v_lshl_add_u64 v[210:211], s[30:31], 0, v[190:191]
	s_add_i32 m0, s40, 0x2000
	s_nop 0
	global_load_lds_dwordx4 v[210:211], off
	v_lshl_add_u64 v[210:211], v[214:215], 0, s[60:61]
	s_mov_b32 m0, s46
	s_nop 0
	global_load_lds_dwordx4 v[210:211], off
	v_lshl_add_u64 v[210:211], v[216:217], 0, s[60:61]
	s_mov_b32 m0, s47
	s_nop 0
	global_load_lds_dwordx4 v[210:211], off
	s_waitcnt vmcnt(8)
	s_waitcnt lgkmcnt(0)
	s_barrier
	s_setprio 1
	s_waitcnt lgkmcnt(0)
	v_mfma_f32_16x16x32_bf16 v[62:65], v[118:121], v[162:165], v[62:65]
	v_mfma_f32_16x16x32_bf16 v[58:61], v[130:133], v[162:165], v[58:61]
	v_mfma_f32_16x16x32_bf16 v[46:49], v[118:121], v[170:173], v[46:49]
	v_mfma_f32_16x16x32_bf16 v[42:45], v[130:133], v[170:173], v[42:45]
	v_mfma_f32_16x16x32_bf16 v[30:33], v[118:121], v[178:181], v[30:33]
	v_mfma_f32_16x16x32_bf16 v[26:29], v[130:133], v[178:181], v[26:29]
	v_mfma_f32_16x16x32_bf16 v[14:17], v[118:121], v[186:189], v[14:17]
	v_mfma_f32_16x16x32_bf16 v[10:13], v[130:133], v[186:189], v[10:13]
	v_mfma_f32_16x16x32_bf16 v[62:65], v[126:129], v[166:169], v[62:65]
	v_mfma_f32_16x16x32_bf16 v[58:61], v[134:137], v[166:169], v[58:61]
	v_mfma_f32_16x16x32_bf16 v[46:49], v[126:129], v[174:177], v[46:49]
	v_mfma_f32_16x16x32_bf16 v[42:45], v[134:137], v[174:177], v[42:45]
	v_mfma_f32_16x16x32_bf16 v[30:33], v[126:129], v[182:185], v[30:33]
	v_mfma_f32_16x16x32_bf16 v[26:29], v[134:137], v[182:185], v[26:29]
	v_mfma_f32_16x16x32_bf16 v[14:17], v[126:129], v[202:205], v[14:17]
	v_mfma_f32_16x16x32_bf16 v[10:13], v[134:137], v[202:205], v[10:13]
	s_setprio 0
	s_setprio 1
	v_mfma_f32_16x16x32_bf16 v[54:57], v[138:141], v[162:165], v[54:57]
	v_mfma_f32_16x16x32_bf16 v[50:53], v[154:157], v[162:165], v[50:53]
	v_mfma_f32_16x16x32_bf16 v[38:41], v[138:141], v[170:173], v[38:41]
	v_mfma_f32_16x16x32_bf16 v[34:37], v[154:157], v[170:173], v[34:37]
	v_mfma_f32_16x16x32_bf16 v[22:25], v[138:141], v[178:181], v[22:25]
	v_mfma_f32_16x16x32_bf16 v[18:21], v[154:157], v[178:181], v[18:21]
	v_mfma_f32_16x16x32_bf16 v[6:9], v[138:141], v[186:189], v[6:9]
	v_mfma_f32_16x16x32_bf16 v[2:5], v[154:157], v[186:189], v[2:5]
	v_mfma_f32_16x16x32_bf16 v[54:57], v[142:145], v[166:169], v[54:57]
	v_mfma_f32_16x16x32_bf16 v[50:53], v[158:161], v[166:169], v[50:53]
	v_mfma_f32_16x16x32_bf16 v[38:41], v[142:145], v[174:177], v[38:41]
	v_mfma_f32_16x16x32_bf16 v[34:37], v[158:161], v[174:177], v[34:37]
	v_mfma_f32_16x16x32_bf16 v[22:25], v[142:145], v[182:185], v[22:25]
	v_mfma_f32_16x16x32_bf16 v[18:21], v[158:161], v[182:185], v[18:21]
	v_mfma_f32_16x16x32_bf16 v[6:9], v[142:145], v[202:205], v[6:9]
	v_mfma_f32_16x16x32_bf16 v[2:5], v[158:161], v[202:205], v[2:5]
	s_setprio 0
	s_barrier
	s_add_i32 s81, s81, 2
	s_add_u32 s4, s4, 0x100
	s_addc_u32 s5, s5, 0
	s_add_u32 s21, s21, 0x100
	s_addc_u32 s27, s27, 0
	s_cmp_gt_u32 s81, 29

; #define PG8_STAGE(bufoff, gbase, voff) do { _Pragma("unroll") for (int _i = 0; _i < 2; ++_i) \
;         __builtin_amdgcn_global_load_lds((const unsigned*)((const char*)(gbase) + (voff)[_i]), (PG8_LAS unsigned*)(lds + (bufoff) + ldsw + _i * 8192), 16, 0, 0); } while (0)
; #define PG8_LDA(dst, b, h) do { _Pragma("unroll") for (int m = 0; m < 4; ++m) _Pragma("unroll") for (int k = 0; k < 2; ++k) dst[m][k] = *(const PG8_LAS bf16x8*)(lds + PG8_SA(b, h) + aoff + m * 2048 + k * 1024); } while (0)
; #define PG8_LDB(dst, b, h) do { _Pragma("unroll") for (int n = 0; n < 2; ++n) _Pragma("unroll") for (int k = 0; k < 2; ++k) dst[n][k] = *(const PG8_LAS bf16x8*)(lds + PG8_SB(b, h) + boff + n * 2048 + k * 1024); } while (0)
; #define PG8_MMA(ai, bj, At, Bt) do { __builtin_amdgcn_s_setprio(1); _Pragma("unroll") for (int m = 0; m < 4; ++m) _Pragma("unroll") for (int n = 0; n < 2; ++n) _Pragma("unroll") for (int k = 0; k < 2; ++k) \
;         acc[ai][bj][m][n] = __builtin_amdgcn_mfma_f32_16x16x32_bf16(Bt[n][k], At[m][k], acc[ai][bj][m][n], 0, 0, 0); __builtin_amdgcn_s_setprio(0); } while (0)
; #define PG8_WAIT_V(n) asm volatile("s_waitcnt vmcnt(" #n ")" ::: "memory")
; #define PG8_WAIT_L(n) asm volatile("s_waitcnt lgkmcnt(" #n ")" ::: "memory")
; #define PG8_BAR __builtin_amdgcn_s_barrier()
; #define PG8_SCHED __builtin_amdgcn_sched_barrier(0)
; template <class Epi, class Sched, bool ALIGN_EPI = false, bool SP2 = false>
; __device__ __forceinline__ void gemm_phase(PG8_LAS unsigned char* lds, const Gemm g, const Sched& S, const Epi& E, int wave_s) {
;     ...
;             PG8_LDB(B0, 0, 0); PG8_LDB(B1, 0, 1); PG8_SCHED; PG8_LDA(At, 0, 0); PG8_STAGE(PG8_SA(1, 1), a1 + hstepA, voffA);
;             PG8_WAIT_V(8); PG8_WAIT_L(0); PG8_BAR; PG8_MMA(0, 0, At, B0); PG8_MMA(0, 1, At, B1); PG8_BAR; PG8_SCHED;
;             PG8_LDA(At, 0, 1); PG8_STAGE(PG8_SB(0, 0), b2, voffB); PG8_STAGE(PG8_SB(0, 1), b2 + hstepB, voffB); PG8_STAGE(PG8_SA(0, 0), a2, voffA);
;             PG8_WAIT_V(8); PG8_WAIT_L(0); PG8_BAR; PG8_MMA(1, 0, At, B0); PG8_MMA(1, 1, At, B1); PG8_BAR; PG8_SCHED;
.LBB0_690:
	s_ashr_i32 s89, s88, 31
	s_lshl_b64 s[2:3], s[88:89], 20
	s_add_u32 s28, s22, s2
	s_addc_u32 s29, s23, s3
	s_and_b64 s[2:3], s[4:5], exec
	s_cselect_b32 s2, s29, s41
	s_cselect_b32 s3, s28, s40
	s_add_u32 s89, s40, 0x100
	s_addc_u32 s91, s41, 0
	s_mov_b32 vcc_lo, -2
	s_add_u32 s4, s30, 0x100
	s_addc_u32 s5, s31, 0
	s_add_i32 vcc_hi, 0, 0x10000
	s_cmp_eq_u32 vcc_lo, 28
	s_cselect_b32 s41, s21, s5
	s_cselect_b32 s40, s20, s4
	s_cselect_b32 s7, s2, s91
	s_cselect_b32 s6, s3, s89
	s_add_i32 s86, 0, 0x14000
	v_add_u32_e32 v142, vcc_hi, v251
	v_add_u32_e32 v158, s86, v251
	ds_read_b128 v[126:129], v142
	ds_read_b128 v[134:137], v142 offset:1024
	ds_read_b128 v[138:141], v142 offset:2048
	ds_read_b128 v[142:145], v142 offset:3072
	ds_read_b128 v[146:149], v158
	ds_read_b128 v[150:153], v158 offset:1024
	ds_read_b128 v[154:157], v158 offset:2048
	ds_read_b128 v[158:161], v158 offset:3072
	v_lshl_add_u64 v[194:195], s[30:31], 0, v[244:245]
	s_add_i32 m0, s36, 0xc000
	ds_read_b128 v[162:165], v252
	ds_read_b128 v[166:169], v252 offset:1024
	ds_read_b128 v[170:173], v252 offset:2048
	ds_read_b128 v[174:177], v252 offset:3072
	ds_read_b128 v[178:181], v252 offset:4096
	ds_read_b128 v[182:185], v252 offset:5120
	ds_read_b128 v[186:189], v252 offset:6144
	ds_read_b128 v[190:193], v252 offset:7168
	global_load_lds_dwordx4 v[194:195], off
	v_lshl_add_u64 v[194:195], s[30:31], 0, v[246:247]
	s_add_i32 m0, s36, 0xe000
	s_nop 0
	global_load_lds_dwordx4 v[194:195], off
	s_waitcnt vmcnt(8)
	s_waitcnt lgkmcnt(0)
	s_barrier
	s_setprio 1
	s_waitcnt lgkmcnt(0)
	v_mfma_f32_16x16x32_bf16 v[130:133], v[126:129], v[162:165], 0
	v_mfma_f32_16x16x32_bf16 v[118:121], v[138:141], v[162:165], 0
	v_mfma_f32_16x16x32_bf16 v[110:113], v[126:129], v[170:173], 0
	v_mfma_f32_16x16x32_bf16 v[98:101], v[138:141], v[170:173], 0
	v_mfma_f32_16x16x32_bf16 v[62:65], v[126:129], v[178:181], 0
	v_mfma_f32_16x16x32_bf16 v[58:61], v[138:141], v[178:181], 0
	v_mfma_f32_16x16x32_bf16 v[46:49], v[126:129], v[186:189], 0
	v_mfma_f32_16x16x32_bf16 v[42:45], v[138:141], v[186:189], 0
	v_mfma_f32_16x16x32_bf16 v[130:133], v[134:137], v[166:169], v[130:133]
	v_mfma_f32_16x16x32_bf16 v[118:121], v[142:145], v[166:169], v[118:121]
	v_mfma_f32_16x16x32_bf16 v[110:113], v[134:137], v[174:177], v[110:113]
	v_mfma_f32_16x16x32_bf16 v[98:101], v[142:145], v[174:177], v[98:101]
	v_mfma_f32_16x16x32_bf16 v[62:65], v[134:137], v[182:185], v[62:65]
	v_mfma_f32_16x16x32_bf16 v[58:61], v[142:145], v[182:185], v[58:61]
	v_mfma_f32_16x16x32_bf16 v[46:49], v[134:137], v[190:193], v[46:49]
	v_mfma_f32_16x16x32_bf16 v[42:45], v[142:145], v[190:193], v[42:45]
	s_setprio 0
	s_setprio 1
	v_mfma_f32_16x16x32_bf16 v[102:105], v[146:149], v[162:165], 0
	v_mfma_f32_16x16x32_bf16 v[74:77], v[154:157], v[162:165], 0
	v_mfma_f32_16x16x32_bf16 v[78:81], v[146:149], v[170:173], 0
	v_mfma_f32_16x16x32_bf16 v[90:93], v[154:157], v[170:173], 0
	v_mfma_f32_16x16x32_bf16 v[34:37], v[146:149], v[178:181], 0
	v_mfma_f32_16x16x32_bf16 v[26:29], v[154:157], v[178:181], 0
	v_mfma_f32_16x16x32_bf16 v[14:17], v[146:149], v[186:189], 0
	v_mfma_f32_16x16x32_bf16 v[2:5], v[154:157], v[186:189], 0
	v_mfma_f32_16x16x32_bf16 v[102:105], v[150:153], v[166:169], v[102:105]
	v_mfma_f32_16x16x32_bf16 v[74:77], v[158:161], v[166:169], v[74:77]
	v_mfma_f32_16x16x32_bf16 v[78:81], v[150:153], v[174:177], v[78:81]
	v_mfma_f32_16x16x32_bf16 v[90:93], v[158:161], v[174:177], v[90:93]
	v_mfma_f32_16x16x32_bf16 v[34:37], v[150:153], v[182:185], v[34:37]
	v_mfma_f32_16x16x32_bf16 v[26:29], v[158:161], v[182:185], v[26:29]
	v_mfma_f32_16x16x32_bf16 v[14:17], v[150:153], v[190:193], v[14:17]
	v_mfma_f32_16x16x32_bf16 v[2:5], v[158:161], v[190:193], v[2:5]
	s_setprio 0
	s_barrier
	s_add_i32 s30, vcc_hi, s35
	v_lshl_add_u64 v[194:195], s[6:7], 0, v[238:239]
	s_mov_b32 m0, s30
	ds_read_b128 v[162:165], v252 offset:16384
	ds_read_b128 v[166:169], v252 offset:17408
	ds_read_b128 v[170:173], v252 offset:18432
	ds_read_b128 v[174:177], v252 offset:19456
	ds_read_b128 v[178:181], v252 offset:20480
	ds_read_b128 v[182:185], v252 offset:21504
	ds_read_b128 v[186:189], v252 offset:22528
	ds_read_b128 v[190:193], v252 offset:23552
	global_load_lds_dwordx4 v[194:195], off
	s_add_i32 m0, s30, 0x2000
	s_add_u32 s30, s6, 0x80000
	v_lshl_add_u64 v[196:197], s[6:7], 0, v[242:243]
	s_addc_u32 s31, s7, 0
	s_add_i32 s86, s86, s35
	global_load_lds_dwordx4 v[196:197], off
	v_lshl_add_u64 v[198:199], s[30:31], 0, v[238:239]
	s_mov_b32 m0, s86
	v_lshl_add_u64 v[200:201], s[40:41], 0, v[240:241]
	global_load_lds_dwordx4 v[198:199], off
	v_lshl_add_u64 v[198:199], s[30:31], 0, v[242:243]
	s_add_i32 m0, s86, 0x2000
	s_nop 0
	global_load_lds_dwordx4 v[198:199], off
	v_lshl_add_u64 v[198:199], s[40:41], 0, v[236:237]
	s_mov_b32 m0, s36
	s_nop 0
	global_load_lds_dwordx4 v[198:199], off
	s_mov_b32 m0, s37
	s_nop 0
	global_load_lds_dwordx4 v[200:201], off
	s_waitcnt vmcnt(8)
	s_waitcnt lgkmcnt(0)
	s_barrier
; #define PG8_STAGE(bufoff, gbase, voff) do { _Pragma("unroll") for (int _i = 0; _i < 2; ++_i) \
;         __builtin_amdgcn_global_load_lds((const unsigned*)((const char*)(gbase) + (voff)[_i]), (PG8_LAS unsigned*)(lds + (bufoff) + ldsw + _i * 8192), 16, 0, 0); } while (0)
; #define PG8_LDA(dst, b, h) do { _Pragma("unroll") for (int m = 0; m < 4; ++m) _Pragma("unroll") for (int k = 0; k < 2; ++k) dst[m][k] = *(const PG8_LAS bf16x8*)(lds + PG8_SA(b, h) + aoff + m * 2048 + k * 1024); } while (0)
; #define PG8_LDB(dst, b, h) do { _Pragma("unroll") for (int n = 0; n < 2; ++n) _Pragma("unroll") for (int k = 0; k < 2; ++k) dst[n][k] = *(const PG8_LAS bf16x8*)(lds + PG8_SB(b, h) + boff + n * 2048 + k * 1024); } while (0)
; #define PG8_MMA(ai, bj, At, Bt) do { __builtin_amdgcn_s_setprio(1); _Pragma("unroll") for (int m = 0; m < 4; ++m) _Pragma("unroll") for (int n = 0; n < 2; ++n) _Pragma("unroll") for (int k = 0; k < 2; ++k) \
;         acc[ai][bj][m][n] = __builtin_amdgcn_mfma_f32_16x16x32_bf16(Bt[n][k], At[m][k], acc[ai][bj][m][n], 0, 0, 0); __builtin_amdgcn_s_setprio(0); } while (0)
; #define PG8_WAIT_V(n) asm volatile("s_waitcnt vmcnt(" #n ")" ::: "memory")
; #define PG8_WAIT_L(n) asm volatile("s_waitcnt lgkmcnt(" #n ")" ::: "memory")
; #define PG8_BAR __builtin_amdgcn_s_barrier()
; #define PG8_SCHED __builtin_amdgcn_sched_barrier(0)
; template <class Epi, class Sched, bool ALIGN_EPI = false, bool SP2 = false>
; __device__ __forceinline__ void gemm_phase(PG8_LAS unsigned char* lds, const Gemm g, const Sched& S, const Epi& E, int wave_s) {
;     ...
;             PG8_WAIT_V(8); PG8_WAIT_L(0); PG8_BAR; PG8_MMA(1, 0, At, B0); PG8_MMA(1, 1, At, B1); PG8_BAR; PG8_SCHED;
;             PG8_LDB(B0, 1, 0); PG8_LDB(B1, 1, 1); PG8_SCHED; PG8_LDA(At, 1, 0); PG8_STAGE(PG8_SA(0, 1), a2 + hstepA, voffA);
;             PG8_WAIT_V(8); PG8_WAIT_L(0); PG8_BAR; PG8_MMA(0, 0, At, B0); PG8_MMA(0, 1, At, B1); PG8_BAR; PG8_SCHED;
	s_setprio 1
	s_waitcnt lgkmcnt(0)
	v_mfma_f32_16x16x32_bf16 v[54:57], v[126:129], v[162:165], 0
	v_mfma_f32_16x16x32_bf16 v[50:53], v[138:141], v[162:165], 0
	v_mfma_f32_16x16x32_bf16 v[38:41], v[126:129], v[170:173], 0
	v_mfma_f32_16x16x32_bf16 v[30:33], v[138:141], v[170:173], 0
	v_mfma_f32_16x16x32_bf16 v[86:89], v[126:129], v[178:181], 0
	v_mfma_f32_16x16x32_bf16 v[122:125], v[138:141], v[178:181], 0
	v_mfma_f32_16x16x32_bf16 v[114:117], v[126:129], v[186:189], 0
	v_mfma_f32_16x16x32_bf16 v[106:109], v[138:141], v[186:189], 0
	v_mfma_f32_16x16x32_bf16 v[54:57], v[134:137], v[166:169], v[54:57]
	v_mfma_f32_16x16x32_bf16 v[50:53], v[142:145], v[166:169], v[50:53]
	v_mfma_f32_16x16x32_bf16 v[38:41], v[134:137], v[174:177], v[38:41]
	v_mfma_f32_16x16x32_bf16 v[30:33], v[142:145], v[174:177], v[30:33]
	v_mfma_f32_16x16x32_bf16 v[86:89], v[134:137], v[182:185], v[86:89]
	v_mfma_f32_16x16x32_bf16 v[122:125], v[142:145], v[182:185], v[122:125]
	v_mfma_f32_16x16x32_bf16 v[114:117], v[134:137], v[190:193], v[114:117]
	v_mfma_f32_16x16x32_bf16 v[106:109], v[142:145], v[190:193], v[106:109]
	s_setprio 0
	s_setprio 1
	v_mfma_f32_16x16x32_bf16 v[22:25], v[146:149], v[162:165], 0
	v_mfma_f32_16x16x32_bf16 v[18:21], v[154:157], v[162:165], 0
	v_mfma_f32_16x16x32_bf16 v[10:13], v[146:149], v[170:173], 0
	v_mfma_f32_16x16x32_bf16 v[6:9], v[154:157], v[170:173], 0
	v_mfma_f32_16x16x32_bf16 v[82:85], v[146:149], v[178:181], 0
	v_mfma_f32_16x16x32_bf16 v[94:97], v[154:157], v[178:181], 0
	v_mfma_f32_16x16x32_bf16 v[70:73], v[146:149], v[186:189], 0
	v_mfma_f32_16x16x32_bf16 v[66:69], v[154:157], v[186:189], 0
	v_mfma_f32_16x16x32_bf16 v[22:25], v[150:153], v[166:169], v[22:25]
	v_mfma_f32_16x16x32_bf16 v[18:21], v[158:161], v[166:169], v[18:21]
	v_mfma_f32_16x16x32_bf16 v[10:13], v[150:153], v[174:177], v[10:13]
	v_mfma_f32_16x16x32_bf16 v[6:9], v[158:161], v[174:177], v[6:9]
	v_mfma_f32_16x16x32_bf16 v[82:85], v[150:153], v[182:185], v[82:85]
	v_mfma_f32_16x16x32_bf16 v[94:97], v[158:161], v[182:185], v[94:97]
	v_mfma_f32_16x16x32_bf16 v[70:73], v[150:153], v[190:193], v[70:73]
	v_mfma_f32_16x16x32_bf16 v[66:69], v[158:161], v[190:193], v[66:69]
	s_setprio 0
	s_barrier
	s_add_i32 s86, 0, 0x18000
	s_add_i32 s87, 0, 0x1c000
	v_add_u32_e32 v142, s86, v251
	v_add_u32_e32 v158, s87, v251
	ds_read_b128 v[126:129], v142
	ds_read_b128 v[134:137], v142 offset:1024
	ds_read_b128 v[138:141], v142 offset:2048
	ds_read_b128 v[142:145], v142 offset:3072
	ds_read_b128 v[146:149], v158
	ds_read_b128 v[150:153], v158 offset:1024
	ds_read_b128 v[154:157], v158 offset:2048
	ds_read_b128 v[158:161], v158 offset:3072
	s_add_u32 s30, s40, 0x4000
	s_addc_u32 s31, s41, 0
	s_mov_b32 m0, s42
	v_lshl_add_u64 v[202:203], s[30:31], 0, v[236:237]
	ds_read_b128 v[162:165], v252 offset:32768
	ds_read_b128 v[166:169], v252 offset:33792
	ds_read_b128 v[170:173], v252 offset:34816
	ds_read_b128 v[174:177], v252 offset:35840
	ds_read_b128 v[178:181], v252 offset:36864
	ds_read_b128 v[182:185], v252 offset:37888
	ds_read_b128 v[186:189], v252 offset:38912
	ds_read_b128 v[190:193], v252 offset:39936
	global_load_lds_dwordx4 v[202:203], off
	v_lshl_add_u64 v[202:203], s[30:31], 0, v[240:241]
	s_mov_b32 m0, s43
	s_nop 0
	global_load_lds_dwordx4 v[202:203], off
	s_waitcnt vmcnt(8)
	s_waitcnt lgkmcnt(0)
	s_barrier
	s_setprio 1
	s_waitcnt lgkmcnt(0)
	v_mfma_f32_16x16x32_bf16 v[130:133], v[126:129], v[162:165], v[130:133]
	v_mfma_f32_16x16x32_bf16 v[118:121], v[138:141], v[162:165], v[118:121]
	v_mfma_f32_16x16x32_bf16 v[110:113], v[126:129], v[170:173], v[110:113]
	v_mfma_f32_16x16x32_bf16 v[98:101], v[138:141], v[170:173], v[98:101]
	v_mfma_f32_16x16x32_bf16 v[62:65], v[126:129], v[178:181], v[62:65]
	v_mfma_f32_16x16x32_bf16 v[58:61], v[138:141], v[178:181], v[58:61]
	v_mfma_f32_16x16x32_bf16 v[46:49], v[126:129], v[186:189], v[46:49]
	v_mfma_f32_16x16x32_bf16 v[42:45], v[138:141], v[186:189], v[42:45]
	v_mfma_f32_16x16x32_bf16 v[130:133], v[134:137], v[166:169], v[130:133]
	v_mfma_f32_16x16x32_bf16 v[118:121], v[142:145], v[166:169], v[118:121]
	v_mfma_f32_16x16x32_bf16 v[110:113], v[134:137], v[174:177], v[110:113]
	v_mfma_f32_16x16x32_bf16 v[98:101], v[142:145], v[174:177], v[98:101]
	v_mfma_f32_16x16x32_bf16 v[62:65], v[134:137], v[182:185], v[62:65]
	v_mfma_f32_16x16x32_bf16 v[58:61], v[142:145], v[182:185], v[58:61]
	v_mfma_f32_16x16x32_bf16 v[46:49], v[134:137], v[190:193], v[46:49]
	v_mfma_f32_16x16x32_bf16 v[42:45], v[142:145], v[190:193], v[42:45]
	s_setprio 0
	s_setprio 1
	v_mfma_f32_16x16x32_bf16 v[102:105], v[146:149], v[162:165], v[102:105]
	v_mfma_f32_16x16x32_bf16 v[74:77], v[154:157], v[162:165], v[74:77]
	v_mfma_f32_16x16x32_bf16 v[78:81], v[146:149], v[170:173], v[78:81]
	v_mfma_f32_16x16x32_bf16 v[90:93], v[154:157], v[170:173], v[90:93]
	v_mfma_f32_16x16x32_bf16 v[34:37], v[146:149], v[178:181], v[34:37]
	v_mfma_f32_16x16x32_bf16 v[26:29], v[154:157], v[178:181], v[26:29]
	v_mfma_f32_16x16x32_bf16 v[14:17], v[146:149], v[186:189], v[14:17]
	v_mfma_f32_16x16x32_bf16 v[2:5], v[154:157], v[186:189], v[2:5]
	v_mfma_f32_16x16x32_bf16 v[102:105], v[150:153], v[166:169], v[102:105]
	v_mfma_f32_16x16x32_bf16 v[74:77], v[158:161], v[166:169], v[74:77]
	v_mfma_f32_16x16x32_bf16 v[78:81], v[150:153], v[174:177], v[78:81]
	v_mfma_f32_16x16x32_bf16 v[90:93], v[158:161], v[174:177], v[90:93]
	v_mfma_f32_16x16x32_bf16 v[34:37], v[150:153], v[182:185], v[34:37]
	v_mfma_f32_16x16x32_bf16 v[26:29], v[158:161], v[182:185], v[26:29]
	v_mfma_f32_16x16x32_bf16 v[14:17], v[150:153], v[190:193], v[14:17]
	v_mfma_f32_16x16x32_bf16 v[2:5], v[158:161], v[190:193], v[2:5]
	s_setprio 0
	s_barrier
; #define PG8_STAGE(bufoff, gbase, voff) do { _Pragma("unroll") for (int _i = 0; _i < 2; ++_i) \
;         __builtin_amdgcn_global_load_lds((const unsigned*)((const char*)(gbase) + (voff)[_i]), (PG8_LAS unsigned*)(lds + (bufoff) + ldsw + _i * 8192), 16, 0, 0); } while (0)
; #define PG8_LDA(dst, b, h) do { _Pragma("unroll") for (int m = 0; m < 4; ++m) _Pragma("unroll") for (int k = 0; k < 2; ++k) dst[m][k] = *(const PG8_LAS bf16x8*)(lds + PG8_SA(b, h) + aoff + m * 2048 + k * 1024); } while (0)
; #define PG8_MMA(ai, bj, At, Bt) do { __builtin_amdgcn_s_setprio(1); _Pragma("unroll") for (int m = 0; m < 4; ++m) _Pragma("unroll") for (int n = 0; n < 2; ++n) _Pragma("unroll") for (int k = 0; k < 2; ++k) \
;         acc[ai][bj][m][n] = __builtin_amdgcn_mfma_f32_16x16x32_bf16(Bt[n][k], At[m][k], acc[ai][bj][m][n], 0, 0, 0); __builtin_amdgcn_s_setprio(0); } while (0)
; #define PG8_WAIT_V(n) asm volatile("s_waitcnt vmcnt(" #n ")" ::: "memory")
; #define PG8_WAIT_L(n) asm volatile("s_waitcnt lgkmcnt(" #n ")" ::: "memory")
; #define PG8_BAR __builtin_amdgcn_s_barrier()
; #define PG8_SCHED __builtin_amdgcn_sched_barrier(0)
; template <class Epi, class Sched, bool ALIGN_EPI = false, bool SP2 = false>
; __device__ __forceinline__ void gemm_phase(PG8_LAS unsigned char* lds, const Gemm g, const Sched& S, const Epi& E, int wave_s) {
;     ...
;         for (int t = 0; t < nt; t += 2) {
;     ...
;             PG8_LDA(At, 1, 1); PG8_STAGE(PG8_SB(1, 0), b3, voffB); PG8_STAGE(PG8_SB(1, 1), b3 + hstepB, voffB); PG8_STAGE(PG8_SA(1, 0), a3, voffA);
;             PG8_WAIT_V(8); PG8_WAIT_L(0); PG8_BAR; PG8_MMA(1, 0, At, B0); PG8_MMA(1, 1, At, B1); PG8_BAR; PG8_SCHED;
	s_add_i32 s30, s86, s35
	v_lshl_add_u64 v[194:195], v[194:195], 0, s[60:61]
	s_mov_b32 m0, s30
	ds_read_b128 v[162:165], v252 offset:49152
	ds_read_b128 v[166:169], v252 offset:50176
	ds_read_b128 v[170:173], v252 offset:51200
	ds_read_b128 v[174:177], v252 offset:52224
	ds_read_b128 v[178:181], v252 offset:53248
	ds_read_b128 v[182:185], v252 offset:54272
	ds_read_b128 v[186:189], v252 offset:55296
	ds_read_b128 v[190:193], v252 offset:56320
	global_load_lds_dwordx4 v[194:195], off
	s_add_i32 m0, s30, 0x2000
	s_add_u32 s6, s6, 0x80080
	v_lshl_add_u64 v[194:195], v[196:197], 0, s[60:61]
	s_addc_u32 s7, s7, 0
	s_add_i32 s30, s87, s35
	global_load_lds_dwordx4 v[194:195], off
	v_lshl_add_u64 v[194:195], s[6:7], 0, v[238:239]
	s_mov_b32 m0, s30
	s_nop 0
	global_load_lds_dwordx4 v[194:195], off
	v_lshl_add_u64 v[194:195], s[6:7], 0, v[242:243]
	s_add_i32 m0, s30, 0x2000
	s_nop 0
	global_load_lds_dwordx4 v[194:195], off
	v_lshl_add_u64 v[194:195], v[198:199], 0, s[60:61]
	s_mov_b32 m0, s77
	s_nop 0
	global_load_lds_dwordx4 v[194:195], off
	v_lshl_add_u64 v[194:195], v[200:201], 0, s[60:61]
	s_mov_b32 m0, s94
	s_nop 0
	global_load_lds_dwordx4 v[194:195], off
	s_waitcnt vmcnt(8)
	s_waitcnt lgkmcnt(0)
	s_barrier
	s_setprio 1
	s_waitcnt lgkmcnt(0)
	v_mfma_f32_16x16x32_bf16 v[54:57], v[126:129], v[162:165], v[54:57]
	v_mfma_f32_16x16x32_bf16 v[50:53], v[138:141], v[162:165], v[50:53]
	v_mfma_f32_16x16x32_bf16 v[38:41], v[126:129], v[170:173], v[38:41]
	v_mfma_f32_16x16x32_bf16 v[30:33], v[138:141], v[170:173], v[30:33]
	v_mfma_f32_16x16x32_bf16 v[86:89], v[126:129], v[178:181], v[86:89]
	v_mfma_f32_16x16x32_bf16 v[122:125], v[138:141], v[178:181], v[122:125]
	v_mfma_f32_16x16x32_bf16 v[114:117], v[126:129], v[186:189], v[114:117]
	v_mfma_f32_16x16x32_bf16 v[106:109], v[138:141], v[186:189], v[106:109]
	v_mfma_f32_16x16x32_bf16 v[54:57], v[134:137], v[166:169], v[54:57]
	v_mfma_f32_16x16x32_bf16 v[50:53], v[142:145], v[166:169], v[50:53]
	v_mfma_f32_16x16x32_bf16 v[38:41], v[134:137], v[174:177], v[38:41]
	v_mfma_f32_16x16x32_bf16 v[30:33], v[142:145], v[174:177], v[30:33]
	v_mfma_f32_16x16x32_bf16 v[86:89], v[134:137], v[182:185], v[86:89]
	v_mfma_f32_16x16x32_bf16 v[122:125], v[142:145], v[182:185], v[122:125]
	v_mfma_f32_16x16x32_bf16 v[114:117], v[134:137], v[190:193], v[114:117]
	v_mfma_f32_16x16x32_bf16 v[106:109], v[142:145], v[190:193], v[106:109]
	s_setprio 0
	s_setprio 1
	v_mfma_f32_16x16x32_bf16 v[22:25], v[146:149], v[162:165], v[22:25]
	v_mfma_f32_16x16x32_bf16 v[18:21], v[154:157], v[162:165], v[18:21]
	v_mfma_f32_16x16x32_bf16 v[10:13], v[146:149], v[170:173], v[10:13]
	v_mfma_f32_16x16x32_bf16 v[6:9], v[154:157], v[170:173], v[6:9]
	v_mfma_f32_16x16x32_bf16 v[82:85], v[146:149], v[178:181], v[82:85]
	v_mfma_f32_16x16x32_bf16 v[94:97], v[154:157], v[178:181], v[94:97]
	v_mfma_f32_16x16x32_bf16 v[70:73], v[146:149], v[186:189], v[70:73]
	v_mfma_f32_16x16x32_bf16 v[66:69], v[154:157], v[186:189], v[66:69]
	v_mfma_f32_16x16x32_bf16 v[22:25], v[150:153], v[166:169], v[22:25]
	v_mfma_f32_16x16x32_bf16 v[18:21], v[158:161], v[166:169], v[18:21]
	v_mfma_f32_16x16x32_bf16 v[10:13], v[150:153], v[174:177], v[10:13]
	v_mfma_f32_16x16x32_bf16 v[6:9], v[158:161], v[174:177], v[6:9]
	v_mfma_f32_16x16x32_bf16 v[82:85], v[150:153], v[182:185], v[82:85]
	v_mfma_f32_16x16x32_bf16 v[94:97], v[158:161], v[182:185], v[94:97]
	v_mfma_f32_16x16x32_bf16 v[70:73], v[150:153], v[190:193], v[70:73]
	v_mfma_f32_16x16x32_bf16 v[66:69], v[158:161], v[190:193], v[66:69]
	s_setprio 0
	s_barrier
	s_add_i32 vcc_lo, vcc_lo, 2
	s_add_u32 s89, s89, 0x100
	s_addc_u32 s91, s91, 0
	s_cmp_gt_u32 vcc_lo, 29
	s_mov_b64 s[30:31], s[4:5]

; #define PG8_STAGE(bufoff, gbase, voff) do { _Pragma("unroll") for (int _i = 0; _i < 2; ++_i) \
;         __builtin_amdgcn_global_load_lds((const unsigned*)((const char*)(gbase) + (voff)[_i]), (PG8_LAS unsigned*)(lds + (bufoff) + ldsw + _i * 8192), 16, 0, 0); } while (0)
; #define PG8_LDA(dst, b, h) do { _Pragma("unroll") for (int m = 0; m < 4; ++m) _Pragma("unroll") for (int k = 0; k < 2; ++k) dst[m][k] = *(const PG8_LAS bf16x8*)(lds + PG8_SA(b, h) + aoff + m * 2048 + k * 1024); } while (0)
; #define PG8_LDB(dst, b, h) do { _Pragma("unroll") for (int n = 0; n < 2; ++n) _Pragma("unroll") for (int k = 0; k < 2; ++k) dst[n][k] = *(const PG8_LAS bf16x8*)(lds + PG8_SB(b, h) + boff + n * 2048 + k * 1024); } while (0)
; #define PG8_MMA(ai, bj, At, Bt) do { __builtin_amdgcn_s_setprio(1); _Pragma("unroll") for (int m = 0; m < 4; ++m) _Pragma("unroll") for (int n = 0; n < 2; ++n) _Pragma("unroll") for (int k = 0; k < 2; ++k) \
;         acc[ai][bj][m][n] = __builtin_amdgcn_mfma_f32_16x16x32_bf16(Bt[n][k], At[m][k], acc[ai][bj][m][n], 0, 0, 0); __builtin_amdgcn_s_setprio(0); } while (0)
; #define PG8_WAIT_V(n) asm volatile("s_waitcnt vmcnt(" #n ")" ::: "memory")
; #define PG8_WAIT_L(n) asm volatile("s_waitcnt lgkmcnt(" #n ")" ::: "memory")
; #define PG8_BAR __builtin_amdgcn_s_barrier()
; #define PG8_SCHED __builtin_amdgcn_sched_barrier(0)
; template <class Epi, class Sched, bool ALIGN_EPI = false, bool SP2 = false>
; __device__ __forceinline__ void gemm_phase(PG8_LAS unsigned char* lds, const Gemm g, const Sched& S, const Epi& E, int wave_s) {
;     ...
;             PG8_LDB(B0, 0, 0); PG8_LDB(B1, 0, 1); PG8_SCHED; PG8_LDA(At, 0, 0); PG8_STAGE(PG8_SA(1, 1), a1 + hstepA, voffA);
;             PG8_WAIT_V(8); PG8_WAIT_L(0); PG8_BAR; PG8_MMA(0, 0, At, B0); PG8_MMA(0, 1, At, B1); PG8_BAR; PG8_SCHED;
;             PG8_LDA(At, 0, 1); PG8_STAGE(PG8_SB(0, 0), b2, voffB); PG8_STAGE(PG8_SB(0, 1), b2 + hstepB, voffB); PG8_STAGE(PG8_SA(0, 0), a2, voffA);
;             PG8_WAIT_V(8); PG8_WAIT_L(0); PG8_BAR; PG8_MMA(1, 0, At, B0); PG8_MMA(1, 1, At, B1); PG8_BAR; PG8_SCHED;
.LBB0_785:
	s_add_u32 s2, s30, 0x100
	s_addc_u32 s3, s31, 0
	s_mov_b32 s81, -2
	s_add_u32 s4, s8, 0x100
	s_addc_u32 s5, s9, 0
	s_add_i32 s84, 0, 0x10000
	s_cmpk_eq_i32 s81, 0x54
	s_cselect_b32 s31, s95, s5
	s_cselect_b32 s30, s94, s4
	s_cselect_b32 s7, s97, s3
	s_cselect_b32 s6, s96, s2
	s_add_i32 s85, 0, 0x14000
	v_add_u32_e32 v110, s84, v211
	v_add_u32_e32 v150, s85, v211
	ds_read_b128 v[78:81], v110
	ds_read_b128 v[86:89], v110 offset:1024
	ds_read_b128 v[102:105], v110 offset:2048
	ds_read_b128 v[110:113], v110 offset:3072
	ds_read_b128 v[122:125], v150
	ds_read_b128 v[134:137], v150 offset:1024
	ds_read_b128 v[146:149], v150 offset:2048
	ds_read_b128 v[150:153], v150 offset:3072
	v_lshl_add_u64 v[206:207], s[8:9], 0, v[198:199]
	s_add_i32 m0, s35, 0xc000
	ds_read_b128 v[162:165], v212
	ds_read_b128 v[166:169], v212 offset:1024
	ds_read_b128 v[170:173], v212 offset:2048
	ds_read_b128 v[174:177], v212 offset:3072
	ds_read_b128 v[178:181], v212 offset:4096
	ds_read_b128 v[182:185], v212 offset:5120
	ds_read_b128 v[186:189], v212 offset:6144
	ds_read_b128 v[202:205], v212 offset:7168
	global_load_lds_dwordx4 v[206:207], off
	v_lshl_add_u64 v[206:207], s[8:9], 0, v[200:201]
	s_add_i32 m0, s35, 0xe000
	s_nop 0
	global_load_lds_dwordx4 v[206:207], off
	s_waitcnt vmcnt(8)
	s_waitcnt lgkmcnt(0)
	s_barrier
	s_setprio 1
	s_waitcnt lgkmcnt(0)
	v_mfma_f32_16x16x32_bf16 v[158:161], v[78:81], v[162:165], 0
	v_mfma_f32_16x16x32_bf16 v[154:157], v[102:105], v[162:165], 0
	v_mfma_f32_16x16x32_bf16 v[130:133], v[78:81], v[170:173], 0
	v_mfma_f32_16x16x32_bf16 v[126:129], v[102:105], v[170:173], 0
	v_mfma_f32_16x16x32_bf16 v[106:109], v[78:81], v[178:181], 0
	v_mfma_f32_16x16x32_bf16 v[98:101], v[102:105], v[178:181], 0
	v_mfma_f32_16x16x32_bf16 v[82:85], v[78:81], v[186:189], 0
	v_mfma_f32_16x16x32_bf16 v[74:77], v[102:105], v[186:189], 0
	v_mfma_f32_16x16x32_bf16 v[158:161], v[86:89], v[166:169], v[158:161]
	v_mfma_f32_16x16x32_bf16 v[154:157], v[110:113], v[166:169], v[154:157]
	v_mfma_f32_16x16x32_bf16 v[130:133], v[86:89], v[174:177], v[130:133]
	v_mfma_f32_16x16x32_bf16 v[126:129], v[110:113], v[174:177], v[126:129]
	v_mfma_f32_16x16x32_bf16 v[106:109], v[86:89], v[182:185], v[106:109]
	v_mfma_f32_16x16x32_bf16 v[98:101], v[110:113], v[182:185], v[98:101]
	v_mfma_f32_16x16x32_bf16 v[82:85], v[86:89], v[202:205], v[82:85]
	v_mfma_f32_16x16x32_bf16 v[74:77], v[110:113], v[202:205], v[74:77]
	s_setprio 0
	s_setprio 1
	v_mfma_f32_16x16x32_bf16 v[142:145], v[122:125], v[162:165], 0
	v_mfma_f32_16x16x32_bf16 v[138:141], v[146:149], v[162:165], 0
	v_mfma_f32_16x16x32_bf16 v[118:121], v[122:125], v[170:173], 0
	v_mfma_f32_16x16x32_bf16 v[114:117], v[146:149], v[170:173], 0
	v_mfma_f32_16x16x32_bf16 v[94:97], v[122:125], v[178:181], 0
	v_mfma_f32_16x16x32_bf16 v[90:93], v[146:149], v[178:181], 0
	v_mfma_f32_16x16x32_bf16 v[70:73], v[122:125], v[186:189], 0
	v_mfma_f32_16x16x32_bf16 v[66:69], v[146:149], v[186:189], 0
	v_mfma_f32_16x16x32_bf16 v[142:145], v[134:137], v[166:169], v[142:145]
	v_mfma_f32_16x16x32_bf16 v[138:141], v[150:153], v[166:169], v[138:141]
	v_mfma_f32_16x16x32_bf16 v[118:121], v[134:137], v[174:177], v[118:121]
	v_mfma_f32_16x16x32_bf16 v[114:117], v[150:153], v[174:177], v[114:117]
	v_mfma_f32_16x16x32_bf16 v[94:97], v[134:137], v[182:185], v[94:97]
	v_mfma_f32_16x16x32_bf16 v[90:93], v[150:153], v[182:185], v[90:93]
	v_mfma_f32_16x16x32_bf16 v[70:73], v[134:137], v[202:205], v[70:73]
	v_mfma_f32_16x16x32_bf16 v[66:69], v[150:153], v[202:205], v[66:69]
	s_setprio 0
	s_barrier
	s_add_i32 s8, s84, s22
	v_lshl_add_u64 v[206:207], s[6:7], 0, v[194:195]
	s_mov_b32 m0, s8
	ds_read_b128 v[162:165], v212 offset:16384
	ds_read_b128 v[166:169], v212 offset:17408
	ds_read_b128 v[170:173], v212 offset:18432
	ds_read_b128 v[174:177], v212 offset:19456
	ds_read_b128 v[178:181], v212 offset:20480
	ds_read_b128 v[182:185], v212 offset:21504
	ds_read_b128 v[186:189], v212 offset:22528
	ds_read_b128 v[202:205], v212 offset:23552
	global_load_lds_dwordx4 v[206:207], off
	s_add_i32 m0, s8, 0x2000
	s_add_u32 s8, s6, 0x160000
	v_lshl_add_u64 v[208:209], s[6:7], 0, v[190:191]
	s_addc_u32 s9, s7, 0
	s_add_i32 s84, s85, s22
	global_load_lds_dwordx4 v[208:209], off
	v_lshl_add_u64 v[214:215], s[8:9], 0, v[194:195]
	s_mov_b32 m0, s84
	v_lshl_add_u64 v[216:217], s[30:31], 0, v[192:193]
	global_load_lds_dwordx4 v[214:215], off
	v_lshl_add_u64 v[214:215], s[8:9], 0, v[190:191]
	s_add_i32 m0, s84, 0x2000
	s_nop 0
	global_load_lds_dwordx4 v[214:215], off
	v_lshl_add_u64 v[214:215], s[30:31], 0, v[196:197]
	s_mov_b32 m0, s35
	s_nop 0
	global_load_lds_dwordx4 v[214:215], off
	s_mov_b32 m0, s36
	s_nop 0
	global_load_lds_dwordx4 v[216:217], off
	s_waitcnt vmcnt(8)
	s_waitcnt lgkmcnt(0)
	s_barrier
; #define PG8_STAGE(bufoff, gbase, voff) do { _Pragma("unroll") for (int _i = 0; _i < 2; ++_i) \
;         __builtin_amdgcn_global_load_lds((const unsigned*)((const char*)(gbase) + (voff)[_i]), (PG8_LAS unsigned*)(lds + (bufoff) + ldsw + _i * 8192), 16, 0, 0); } while (0)
; #define PG8_LDA(dst, b, h) do { _Pragma("unroll") for (int m = 0; m < 4; ++m) _Pragma("unroll") for (int k = 0; k < 2; ++k) dst[m][k] = *(const PG8_LAS bf16x8*)(lds + PG8_SA(b, h) + aoff + m * 2048 + k * 1024); } while (0)
; #define PG8_LDB(dst, b, h) do { _Pragma("unroll") for (int n = 0; n < 2; ++n) _Pragma("unroll") for (int k = 0; k < 2; ++k) dst[n][k] = *(const PG8_LAS bf16x8*)(lds + PG8_SB(b, h) + boff + n * 2048 + k * 1024); } while (0)
; #define PG8_MMA(ai, bj, At, Bt) do { __builtin_amdgcn_s_setprio(1); _Pragma("unroll") for (int m = 0; m < 4; ++m) _Pragma("unroll") for (int n = 0; n < 2; ++n) _Pragma("unroll") for (int k = 0; k < 2; ++k) \
;         acc[ai][bj][m][n] = __builtin_amdgcn_mfma_f32_16x16x32_bf16(Bt[n][k], At[m][k], acc[ai][bj][m][n], 0, 0, 0); __builtin_amdgcn_s_setprio(0); } while (0)
; #define PG8_WAIT_V(n) asm volatile("s_waitcnt vmcnt(" #n ")" ::: "memory")
; #define PG8_WAIT_L(n) asm volatile("s_waitcnt lgkmcnt(" #n ")" ::: "memory")
; #define PG8_BAR __builtin_amdgcn_s_barrier()
; #define PG8_SCHED __builtin_amdgcn_sched_barrier(0)
; template <class Epi, class Sched, bool ALIGN_EPI = false, bool SP2 = false>
; __device__ __forceinline__ void gemm_phase(PG8_LAS unsigned char* lds, const Gemm g, const Sched& S, const Epi& E, int wave_s) {
;     ...
;             PG8_WAIT_V(8); PG8_WAIT_L(0); PG8_BAR; PG8_MMA(1, 0, At, B0); PG8_MMA(1, 1, At, B1); PG8_BAR; PG8_SCHED;
;             PG8_LDB(B0, 1, 0); PG8_LDB(B1, 1, 1); PG8_SCHED; PG8_LDA(At, 1, 0); PG8_STAGE(PG8_SA(0, 1), a2 + hstepA, voffA);
;             PG8_WAIT_V(8); PG8_WAIT_L(0); PG8_BAR; PG8_MMA(0, 0, At, B0); PG8_MMA(0, 1, At, B1); PG8_BAR; PG8_SCHED;
	s_setprio 1
	s_waitcnt lgkmcnt(0)
	v_mfma_f32_16x16x32_bf16 v[62:65], v[78:81], v[162:165], 0
	v_mfma_f32_16x16x32_bf16 v[58:61], v[102:105], v[162:165], 0
	v_mfma_f32_16x16x32_bf16 v[46:49], v[78:81], v[170:173], 0
	v_mfma_f32_16x16x32_bf16 v[42:45], v[102:105], v[170:173], 0
	v_mfma_f32_16x16x32_bf16 v[30:33], v[78:81], v[178:181], 0
	v_mfma_f32_16x16x32_bf16 v[26:29], v[102:105], v[178:181], 0
	v_mfma_f32_16x16x32_bf16 v[14:17], v[78:81], v[186:189], 0
	v_mfma_f32_16x16x32_bf16 v[10:13], v[102:105], v[186:189], 0
	v_mfma_f32_16x16x32_bf16 v[62:65], v[86:89], v[166:169], v[62:65]
	v_mfma_f32_16x16x32_bf16 v[58:61], v[110:113], v[166:169], v[58:61]
	v_mfma_f32_16x16x32_bf16 v[46:49], v[86:89], v[174:177], v[46:49]
	v_mfma_f32_16x16x32_bf16 v[42:45], v[110:113], v[174:177], v[42:45]
	v_mfma_f32_16x16x32_bf16 v[30:33], v[86:89], v[182:185], v[30:33]
	v_mfma_f32_16x16x32_bf16 v[26:29], v[110:113], v[182:185], v[26:29]
	v_mfma_f32_16x16x32_bf16 v[14:17], v[86:89], v[202:205], v[14:17]
	v_mfma_f32_16x16x32_bf16 v[10:13], v[110:113], v[202:205], v[10:13]
	s_setprio 0
	s_setprio 1
	v_mfma_f32_16x16x32_bf16 v[54:57], v[122:125], v[162:165], 0
	v_mfma_f32_16x16x32_bf16 v[50:53], v[146:149], v[162:165], 0
	v_mfma_f32_16x16x32_bf16 v[38:41], v[122:125], v[170:173], 0
	v_mfma_f32_16x16x32_bf16 v[34:37], v[146:149], v[170:173], 0
	v_mfma_f32_16x16x32_bf16 v[22:25], v[122:125], v[178:181], 0
	v_mfma_f32_16x16x32_bf16 v[18:21], v[146:149], v[178:181], 0
	v_mfma_f32_16x16x32_bf16 v[6:9], v[122:125], v[186:189], 0
	v_mfma_f32_16x16x32_bf16 v[2:5], v[146:149], v[186:189], 0
	v_mfma_f32_16x16x32_bf16 v[54:57], v[134:137], v[166:169], v[54:57]
	v_mfma_f32_16x16x32_bf16 v[50:53], v[150:153], v[166:169], v[50:53]
	v_mfma_f32_16x16x32_bf16 v[38:41], v[134:137], v[174:177], v[38:41]
	v_mfma_f32_16x16x32_bf16 v[34:37], v[150:153], v[174:177], v[34:37]
	v_mfma_f32_16x16x32_bf16 v[22:25], v[134:137], v[182:185], v[22:25]
	v_mfma_f32_16x16x32_bf16 v[18:21], v[150:153], v[182:185], v[18:21]
	v_mfma_f32_16x16x32_bf16 v[6:9], v[134:137], v[202:205], v[6:9]
	v_mfma_f32_16x16x32_bf16 v[2:5], v[150:153], v[202:205], v[2:5]
	s_setprio 0
	s_barrier
	s_add_i32 s84, 0, 0x18000
	s_add_i32 s85, 0, 0x1c000
	v_add_u32_e32 v110, s84, v211
	v_add_u32_e32 v150, s85, v211
	ds_read_b128 v[78:81], v110
	ds_read_b128 v[86:89], v110 offset:1024
	ds_read_b128 v[102:105], v110 offset:2048
	ds_read_b128 v[110:113], v110 offset:3072
	ds_read_b128 v[122:125], v150
	ds_read_b128 v[134:137], v150 offset:1024
	ds_read_b128 v[146:149], v150 offset:2048
	ds_read_b128 v[150:153], v150 offset:3072
	s_add_u32 s8, s30, 0x160000
	s_addc_u32 s9, s31, 0
	s_mov_b32 m0, s37
	v_lshl_add_u64 v[218:219], s[8:9], 0, v[196:197]
	ds_read_b128 v[162:165], v212 offset:32768
	ds_read_b128 v[166:169], v212 offset:33792
	ds_read_b128 v[170:173], v212 offset:34816
	ds_read_b128 v[174:177], v212 offset:35840
	ds_read_b128 v[178:181], v212 offset:36864
	ds_read_b128 v[182:185], v212 offset:37888
	ds_read_b128 v[186:189], v212 offset:38912
	ds_read_b128 v[202:205], v212 offset:39936
	global_load_lds_dwordx4 v[218:219], off
	v_lshl_add_u64 v[218:219], s[8:9], 0, v[192:193]
	s_mov_b32 m0, s40
	s_nop 0
	global_load_lds_dwordx4 v[218:219], off
	s_waitcnt vmcnt(8)
	s_waitcnt lgkmcnt(0)
	s_barrier
	s_setprio 1
	s_waitcnt lgkmcnt(0)
	v_mfma_f32_16x16x32_bf16 v[158:161], v[78:81], v[162:165], v[158:161]
	v_mfma_f32_16x16x32_bf16 v[154:157], v[102:105], v[162:165], v[154:157]
	v_mfma_f32_16x16x32_bf16 v[130:133], v[78:81], v[170:173], v[130:133]
	v_mfma_f32_16x16x32_bf16 v[126:129], v[102:105], v[170:173], v[126:129]
	v_mfma_f32_16x16x32_bf16 v[106:109], v[78:81], v[178:181], v[106:109]
	v_mfma_f32_16x16x32_bf16 v[98:101], v[102:105], v[178:181], v[98:101]
	v_mfma_f32_16x16x32_bf16 v[82:85], v[78:81], v[186:189], v[82:85]
	v_mfma_f32_16x16x32_bf16 v[74:77], v[102:105], v[186:189], v[74:77]
	v_mfma_f32_16x16x32_bf16 v[158:161], v[86:89], v[166:169], v[158:161]
	v_mfma_f32_16x16x32_bf16 v[154:157], v[110:113], v[166:169], v[154:157]
	v_mfma_f32_16x16x32_bf16 v[130:133], v[86:89], v[174:177], v[130:133]
	v_mfma_f32_16x16x32_bf16 v[126:129], v[110:113], v[174:177], v[126:129]
	v_mfma_f32_16x16x32_bf16 v[106:109], v[86:89], v[182:185], v[106:109]
	v_mfma_f32_16x16x32_bf16 v[98:101], v[110:113], v[182:185], v[98:101]
	v_mfma_f32_16x16x32_bf16 v[82:85], v[86:89], v[202:205], v[82:85]
	v_mfma_f32_16x16x32_bf16 v[74:77], v[110:113], v[202:205], v[74:77]
	s_setprio 0
	s_setprio 1
	v_mfma_f32_16x16x32_bf16 v[142:145], v[122:125], v[162:165], v[142:145]
	v_mfma_f32_16x16x32_bf16 v[138:141], v[146:149], v[162:165], v[138:141]
	v_mfma_f32_16x16x32_bf16 v[118:121], v[122:125], v[170:173], v[118:121]
	v_mfma_f32_16x16x32_bf16 v[114:117], v[146:149], v[170:173], v[114:117]
	v_mfma_f32_16x16x32_bf16 v[94:97], v[122:125], v[178:181], v[94:97]
	v_mfma_f32_16x16x32_bf16 v[90:93], v[146:149], v[178:181], v[90:93]
	v_mfma_f32_16x16x32_bf16 v[70:73], v[122:125], v[186:189], v[70:73]
	v_mfma_f32_16x16x32_bf16 v[66:69], v[146:149], v[186:189], v[66:69]
	v_mfma_f32_16x16x32_bf16 v[142:145], v[134:137], v[166:169], v[142:145]
	v_mfma_f32_16x16x32_bf16 v[138:141], v[150:153], v[166:169], v[138:141]
	v_mfma_f32_16x16x32_bf16 v[118:121], v[134:137], v[174:177], v[118:121]
	v_mfma_f32_16x16x32_bf16 v[114:117], v[150:153], v[174:177], v[114:117]
	v_mfma_f32_16x16x32_bf16 v[94:97], v[134:137], v[182:185], v[94:97]
	v_mfma_f32_16x16x32_bf16 v[90:93], v[150:153], v[182:185], v[90:93]
	v_mfma_f32_16x16x32_bf16 v[70:73], v[134:137], v[202:205], v[70:73]
	v_mfma_f32_16x16x32_bf16 v[66:69], v[150:153], v[202:205], v[66:69]
	s_setprio 0
	s_barrier
; #define PG8_STAGE(bufoff, gbase, voff) do { _Pragma("unroll") for (int _i = 0; _i < 2; ++_i) \
;         __builtin_amdgcn_global_load_lds((const unsigned*)((const char*)(gbase) + (voff)[_i]), (PG8_LAS unsigned*)(lds + (bufoff) + ldsw + _i * 8192), 16, 0, 0); } while (0)
; #define PG8_LDA(dst, b, h) do { _Pragma("unroll") for (int m = 0; m < 4; ++m) _Pragma("unroll") for (int k = 0; k < 2; ++k) dst[m][k] = *(const PG8_LAS bf16x8*)(lds + PG8_SA(b, h) + aoff + m * 2048 + k * 1024); } while (0)
; #define PG8_MMA(ai, bj, At, Bt) do { __builtin_amdgcn_s_setprio(1); _Pragma("unroll") for (int m = 0; m < 4; ++m) _Pragma("unroll") for (int n = 0; n < 2; ++n) _Pragma("unroll") for (int k = 0; k < 2; ++k) \
;         acc[ai][bj][m][n] = __builtin_amdgcn_mfma_f32_16x16x32_bf16(Bt[n][k], At[m][k], acc[ai][bj][m][n], 0, 0, 0); __builtin_amdgcn_s_setprio(0); } while (0)
; #define PG8_WAIT_V(n) asm volatile("s_waitcnt vmcnt(" #n ")" ::: "memory")
; #define PG8_WAIT_L(n) asm volatile("s_waitcnt lgkmcnt(" #n ")" ::: "memory")
; #define PG8_BAR __builtin_amdgcn_s_barrier()
; #define PG8_SCHED __builtin_amdgcn_sched_barrier(0)
; template <class Epi, class Sched, bool ALIGN_EPI = false, bool SP2 = false>
; __device__ __forceinline__ void gemm_phase(PG8_LAS unsigned char* lds, const Gemm g, const Sched& S, const Epi& E, int wave_s) {
;     ...
;         for (int t = 0; t < nt; t += 2) {
;     ...
;             PG8_LDA(At, 1, 1); PG8_STAGE(PG8_SB(1, 0), b3, voffB); PG8_STAGE(PG8_SB(1, 1), b3 + hstepB, voffB); PG8_STAGE(PG8_SA(1, 0), a3, voffA);
;             PG8_WAIT_V(8); PG8_WAIT_L(0); PG8_BAR; PG8_MMA(1, 0, At, B0); PG8_MMA(1, 1, At, B1); PG8_BAR; PG8_SCHED;
	s_add_i32 s8, s84, s22
	v_lshl_add_u64 v[206:207], v[206:207], 0, s[60:61]
	s_mov_b32 m0, s8
	ds_read_b128 v[162:165], v212 offset:49152
	ds_read_b128 v[166:169], v212 offset:50176
	ds_read_b128 v[170:173], v212 offset:51200
	ds_read_b128 v[174:177], v212 offset:52224
	ds_read_b128 v[178:181], v212 offset:53248
	ds_read_b128 v[182:185], v212 offset:54272
	ds_read_b128 v[186:189], v212 offset:55296
	ds_read_b128 v[202:205], v212 offset:56320
	global_load_lds_dwordx4 v[206:207], off
	s_add_i32 m0, s8, 0x2000
	s_add_u32 s6, s6, 0x160080
	v_lshl_add_u64 v[206:207], v[208:209], 0, s[60:61]
	s_addc_u32 s7, s7, 0
	s_add_i32 s8, s85, s22
	global_load_lds_dwordx4 v[206:207], off
	v_lshl_add_u64 v[206:207], s[6:7], 0, v[194:195]
	s_mov_b32 m0, s8
	s_nop 0
	global_load_lds_dwordx4 v[206:207], off
	v_lshl_add_u64 v[206:207], s[6:7], 0, v[190:191]
	s_add_i32 m0, s8, 0x2000
	s_nop 0
	global_load_lds_dwordx4 v[206:207], off
	v_lshl_add_u64 v[206:207], v[214:215], 0, s[60:61]
	s_mov_b32 m0, s44
	s_nop 0
	global_load_lds_dwordx4 v[206:207], off
	v_lshl_add_u64 v[206:207], v[216:217], 0, s[60:61]
	s_mov_b32 m0, s45
	s_nop 0
	global_load_lds_dwordx4 v[206:207], off
	s_waitcnt vmcnt(8)
	s_waitcnt lgkmcnt(0)
	s_barrier
	s_setprio 1
	s_waitcnt lgkmcnt(0)
	v_mfma_f32_16x16x32_bf16 v[62:65], v[78:81], v[162:165], v[62:65]
	v_mfma_f32_16x16x32_bf16 v[58:61], v[102:105], v[162:165], v[58:61]
	v_mfma_f32_16x16x32_bf16 v[46:49], v[78:81], v[170:173], v[46:49]
	v_mfma_f32_16x16x32_bf16 v[42:45], v[102:105], v[170:173], v[42:45]
	v_mfma_f32_16x16x32_bf16 v[30:33], v[78:81], v[178:181], v[30:33]
	v_mfma_f32_16x16x32_bf16 v[26:29], v[102:105], v[178:181], v[26:29]
	v_mfma_f32_16x16x32_bf16 v[14:17], v[78:81], v[186:189], v[14:17]
	v_mfma_f32_16x16x32_bf16 v[10:13], v[102:105], v[186:189], v[10:13]
	v_mfma_f32_16x16x32_bf16 v[62:65], v[86:89], v[166:169], v[62:65]
	v_mfma_f32_16x16x32_bf16 v[58:61], v[110:113], v[166:169], v[58:61]
	v_mfma_f32_16x16x32_bf16 v[46:49], v[86:89], v[174:177], v[46:49]
	v_mfma_f32_16x16x32_bf16 v[42:45], v[110:113], v[174:177], v[42:45]
	v_mfma_f32_16x16x32_bf16 v[30:33], v[86:89], v[182:185], v[30:33]
	v_mfma_f32_16x16x32_bf16 v[26:29], v[110:113], v[182:185], v[26:29]
	v_mfma_f32_16x16x32_bf16 v[14:17], v[86:89], v[202:205], v[14:17]
	v_mfma_f32_16x16x32_bf16 v[10:13], v[110:113], v[202:205], v[10:13]
	s_setprio 0
	s_setprio 1
	v_mfma_f32_16x16x32_bf16 v[54:57], v[122:125], v[162:165], v[54:57]
	v_mfma_f32_16x16x32_bf16 v[50:53], v[146:149], v[162:165], v[50:53]
	v_mfma_f32_16x16x32_bf16 v[38:41], v[122:125], v[170:173], v[38:41]
	v_mfma_f32_16x16x32_bf16 v[34:37], v[146:149], v[170:173], v[34:37]
	v_mfma_f32_16x16x32_bf16 v[22:25], v[122:125], v[178:181], v[22:25]
	v_mfma_f32_16x16x32_bf16 v[18:21], v[146:149], v[178:181], v[18:21]
	v_mfma_f32_16x16x32_bf16 v[6:9], v[122:125], v[186:189], v[6:9]
	v_mfma_f32_16x16x32_bf16 v[2:5], v[146:149], v[186:189], v[2:5]
	v_mfma_f32_16x16x32_bf16 v[54:57], v[134:137], v[166:169], v[54:57]
	v_mfma_f32_16x16x32_bf16 v[50:53], v[150:153], v[166:169], v[50:53]
	v_mfma_f32_16x16x32_bf16 v[38:41], v[134:137], v[174:177], v[38:41]
	v_mfma_f32_16x16x32_bf16 v[34:37], v[150:153], v[174:177], v[34:37]
	v_mfma_f32_16x16x32_bf16 v[22:25], v[134:137], v[182:185], v[22:25]
	v_mfma_f32_16x16x32_bf16 v[18:21], v[150:153], v[182:185], v[18:21]
	v_mfma_f32_16x16x32_bf16 v[6:9], v[134:137], v[202:205], v[6:9]
	v_mfma_f32_16x16x32_bf16 v[2:5], v[150:153], v[202:205], v[2:5]
	s_setprio 0
	s_barrier
	s_add_i32 s81, s81, 2
	s_add_u32 s2, s2, 0x100
	s_addc_u32 s3, s3, 0
	s_cmpk_gt_u32 s81, 0x55
	s_mov_b64 s[8:9], s[4:5]
